# attention schedule variant: MERGEW=2
# baseline (speedup 1.0000x reference)
; __device__ __forceinline__ int v_st(int k, int c) { const int kk = (k & ~0xC) | ((k & 4) << 1) | ((k & 8) >> 1); return ((kk >> 3) * 4 + (c >> 5)) * 512 + ((kk & 7) * 32 + (c & 31)) * 2; }
; __device__ __forceinline__ int v_rd_base(int lane) { return ((lane & 3) << 3) | (((lane >> 2) & 3) << 6) | (((lane >> 4) & 1) << 5) | (((lane >> 5) & 1) << 8); }
; __device__ void phase_attn(const Params& p, char* lds) {
;     ...
;   const int tid = threadIdx.x, wid = tid >> 6, lane = tid & 63, r32 = lane & 31, hi = lane >> 5;
;   char* V_lds = lds; char* K_lds = lds + AT_KOFF;
;   float* wsl = (float*)(lds + AT_WOFF) + wid * 64; float* li_l = wsl; float* al_l = wsl + 32;
;   const int skey = tid >> 3, sc8 = (tid & 7) * 8;
;   const int pkey = (tid & 255) >> 2, pc8 = (tid & 3) * 8;
;   const int vst = v_st(skey, sc8), kst = skey * AT_KROW + sc8 * 2, pst = pkey * AT_KROW + (64 + pc8) * 2;
;   const int vb0 = (int)(uintptr_t)V_lds + v_rd_base(lane);
;   const int nitems = NB * 16 * 32;
;   const int xcd = blockIdx.x & 7, slot = blockIdx.x >> 3, per = gridDim.x >> 3;
.LBB0_991:
	s_or_b64 exec, exec, s[4:5]
	s_cmpk_gt_u32 s3, 0xfff
	s_waitcnt vmcnt(7)
	v_and_b32_e32 v128, 56, v183
	v_lshlrev_b32_e32 v168, 11, v161
	s_barrier
	v_and_b32_e32 v175, 63, v178
	v_and_b32_e32 v183, 31, v178
	v_lshrrev_b32_e32 v228, 5, v175
	v_readfirstlane_b32 s14, v178
	v_lshrrev_b32_e32 v229, 3, v178
	v_and_b32_e32 v230, 7, v178
	s_lshr_b32 s14, s14, 6
	s_lshr_b32 s15, s14, 2
	s_and_b32 s43, s3, 7
	s_mov_b32 s23, 0x453a4f54
	v_lshlrev_b32_e32 v129, 4, v230
	v_lshl_or_b32 v129, v229, 12, v129
	v_mul_u32_u24_e32 v167, 0xd0, v229
	v_lshl_add_u32 v167, v230, 4, v167
	v_add_u32_e32 v167, 0x10000, v167
	v_lshrrev_b32_e32 v131, 3, v229
	v_lshlrev_b32_e32 v131, 11, v131
	v_lshrrev_b32_e32 v174, 2, v230
	v_lshl_or_b32 v131, v174, 9, v131
	v_and_b32_e32 v174, 7, v229
	v_lshl_or_b32 v131, v174, 6, v131
	v_and_b32_e32 v174, 3, v178
	v_lshl_or_b32 v131, v174, 4, v131
	v_bfe_u32 v229, v178, 2, 6
	v_lshlrev_b32_e32 v130, 4, v174
	v_lshl_or_b32 v130, v229, 6, v130
	v_mul_u32_u24_e32 v169, 0xd0, v229
	v_lshl_add_u32 v169, v174, 4, v169
	v_add_u32_e32 v169, 0x10080, v169
	v_mul_u32_u24_e32 v170, 0xd0, v183
	v_lshl_add_u32 v170, v228, 4, v170
	v_add_u32_e32 v170, 0x10000, v170
	v_and_b32_e32 v174, 3, v175
	v_lshlrev_b32_e32 v174, 3, v174
	v_mov_b32_e32 v171, v174
	v_bfe_u32 v174, v175, 2, 2
	v_lshl_or_b32 v171, v174, 6, v171
	v_bfe_u32 v174, v175, 4, 1
	v_lshl_or_b32 v171, v174, 5, v171
	v_lshl_or_b32 v171, v228, 8, v171
	s_lshl_b32 s16, s14, 5
	v_add_u32_e32 v174, s16, v183
	v_mul_u32_u24_e32 v234, 0xc00, v174
	v_lshl_add_u32 v234, v228, 4, v234
	v_lshlrev_b32_e32 v235, 2, v228
	v_add_u32_e32 v235, s16, v235
	v_lshlrev_b32_e32 v235, 11, v235
	v_lshl_add_u32 v235, v183, 1, v235
	s_lshl_b32 s17, s14, 8
	s_add_i32 s17, s17, 0x1d000
	v_lshl_add_u32 v244, v183, 2, s17
	v_lshl_add_u32 v245, v228, 4, s17
	s_add_u32 s34, s86, 0x3d796000
	s_addc_u32 s35, s87, 0
	s_lshr_b32 s12, s3, 3

; __device__ __forceinline__ void at_qkt(f32x16& p0, f32x16& p1, const char* Ks, const bf16x8* qr, int r32, int hi, float negm) {
; #pragma unroll
;   for (int r = 0; r < 16; ++r) { p0[r] = negm; p1[r] = negm; }
; #pragma unroll
;   for (int d0 = 0; d0 < 6; ++d0) {
;     const bf16x8 b0 = *(const bf16x8*)(Ks + r32 * AT_KROW + d0 * 32 + hi * 16);
;     const bf16x8 b1 = *(const bf16x8*)(Ks + (32 + r32) * AT_KROW + d0 * 32 + hi * 16);
;     p0 = MFMA(b0, qr[d0], p0);
;     p1 = MFMA(b1, qr[d0], p1);
;   }
; }
; __device__ __forceinline__ int v_st(int k, int c) { const int kk = (k & ~0xC) | ((k & 4) << 1) | ((k & 8) >> 1); return ((kk >> 3) * 4 + (c >> 5)) * 512 + ((kk & 7) * 32 + (c & 31)) * 2; }
; __device__ __forceinline__ int v_rd_base(int lane) { return ((lane & 3) << 3) | (((lane >> 2) & 3) << 6) | (((lane >> 4) & 1) << 5) | (((lane >> 5) & 1) << 8); }
; template <int OFF> __device__ __forceinline__ s16x4 tr_read(int vb) {
;   s16x4 r; asm volatile("ds_read_b64_tr_b16 %0, %1 offset:%2" : "=&v"(r) : "v"(vb), "i"(OFF) : "memory"); return r;
; }
; template <int D0> __device__ __forceinline__ void pv_one(f32x16& od, int vb, bf16x8 pa0, bf16x8 pa1, bf16x8 pa2, bf16x8 pa3) {
;   const s16x4 l0 = tr_read<v_rd_off(D0, 0, 0)>(vb), h0 = tr_read<v_rd_off(D0, 0, 1)>(vb), l1 = tr_read<v_rd_off(D0, 1, 0)>(vb), h1 = tr_read<v_rd_off(D0, 1, 1)>(vb);
;   const s16x4 l2 = tr_read<v_rd_off(D0, 2, 0)>(vb), h2 = tr_read<v_rd_off(D0, 2, 1)>(vb), l3 = tr_read<v_rd_off(D0, 3, 0)>(vb), h3 = tr_read<v_rd_off(D0, 3, 1)>(vb);
;   asm volatile("s_waitcnt lgkmcnt(0)" ::: "memory"); SBAR();
;     ...
;   od = MFMA(pa0, PK(l0, h0), od);
;   od = MFMA(pa1, PK(l1, h1), od);
;   od = MFMA(pa2, PK(l2, h2), od);
;   od = MFMA(pa3, PK(l3, h3), od);
;     ...
; }
; __device__ void phase_attn(const Params& p, char* lds) {
;     ...
;     for (int j = 1; j + 1 < NT; j += 2) {
;       SBAR(); at_qkt(pB0, pB1, K_lds + AT_SHMK, qr, r32, hi, -m_reg);
;       at_finishSM(pA0, pA1, alA, l_reg, pa0, pa1, pa2, pa3); SBAR();
;       SLOAD(1, (j + 2) * 64); SBAR();
;       pv_d0(o, vb0, pa0, pa1, pa2, pa3); at_partialSM(pB0, pB1, m_reg, alB, false);
;       __syncthreads(); SWAIT(); SWRITE(0, 0);
;       RESC(alB); __syncthreads();
;       SBAR(); at_qkt(pA0, pA1, K_lds, qr, r32, hi, -m_reg);
;       at_finishSM(pB0, pB1, alB, l_reg, pa0, pa1, pa2, pa3); SBAR();
;       if (j + 3 < NT) SLOAD(0, (j + 3) * 64); SBAR();
.Lat_loop:
	ds_read_b128 v[200:203], v170 offset:13376
	ds_read_b128 v[204:207], v170 offset:20032
	s_waitcnt lgkmcnt(4)
	v_mfma_f32_32x32x16_bf16 v[32:47], v[184:187], v[80:83], v[64:79]
	v_mfma_f32_32x32x16_bf16 v[48:63], v[188:191], v[80:83], v[64:79]
	ds_read_b128 v[208:211], v170 offset:13408
	ds_read_b128 v[212:215], v170 offset:20064
	s_waitcnt lgkmcnt(4)
	v_mfma_f32_32x32x16_bf16 v[32:47], v[192:195], v[84:87], v[32:47]
	v_mfma_f32_32x32x16_bf16 v[48:63], v[196:199], v[84:87], v[48:63]
	ds_read_b128 v[184:187], v170 offset:13440
	ds_read_b128 v[188:191], v170 offset:20096
	s_waitcnt lgkmcnt(4)
	v_mfma_f32_32x32x16_bf16 v[32:47], v[200:203], v[88:91], v[32:47]
	v_mfma_f32_32x32x16_bf16 v[48:63], v[204:207], v[88:91], v[48:63]
	ds_read_b128 v[192:195], v170 offset:13472
	ds_read_b128 v[196:199], v170 offset:20128
	s_waitcnt lgkmcnt(4)
	v_mfma_f32_32x32x16_bf16 v[32:47], v[208:211], v[92:95], v[32:47]
	v_mfma_f32_32x32x16_bf16 v[48:63], v[212:215], v[92:95], v[48:63]
	ds_read_b64_tr_b16 v[148:149], v171 offset:0
	ds_read_b64_tr_b16 v[150:151], v171 offset:2048
	ds_read_b64_tr_b16 v[152:153], v171 offset:4096
	ds_read_b64_tr_b16 v[154:155], v171 offset:6144
	s_waitcnt lgkmcnt(6)
	v_mfma_f32_32x32x16_bf16 v[32:47], v[184:187], v[96:99], v[32:47]
	v_mfma_f32_32x32x16_bf16 v[48:63], v[188:191], v[96:99], v[48:63]
	ds_read_b64_tr_b16 v[156:157], v171 offset:8192
	ds_read_b64_tr_b16 v[158:159], v171 offset:10240
	ds_read_b64_tr_b16 v[216:217], v171 offset:12288
	ds_read_b64_tr_b16 v[218:219], v171 offset:14336
	s_waitcnt lgkmcnt(8)
	v_mfma_f32_32x32x16_bf16 v[32:47], v[192:195], v[100:103], v[32:47]
	v_mfma_f32_32x32x16_bf16 v[48:63], v[196:199], v[100:103], v[48:63]
	ds_read_b64_tr_b16 v[220:221], v171 offset:512
	ds_read_b64_tr_b16 v[222:223], v171 offset:2560
	ds_read_b64_tr_b16 v[224:225], v171 offset:4608
	ds_read_b64_tr_b16 v[226:227], v171 offset:6656
	s_waitcnt lgkmcnt(8)
	v_mfma_f32_32x32x16_bf16 v[0:15], v[104:107], v[148:151], v[0:15]
	v_mfma_f32_32x32x16_bf16 v[0:15], v[108:111], v[152:155], v[0:15]
	ds_read_b64_tr_b16 v[236:237], v171 offset:8704
	ds_read_b64_tr_b16 v[238:239], v171 offset:10752
	ds_read_b64_tr_b16 v[240:241], v171 offset:12800
	ds_read_b64_tr_b16 v[242:243], v171 offset:14848
	s_waitcnt lgkmcnt(8)
	v_mfma_f32_32x32x16_bf16 v[0:15], v[112:115], v[156:159], v[0:15]
	v_mfma_f32_32x32x16_bf16 v[0:15], v[116:119], v[216:219], v[0:15]
	s_waitcnt lgkmcnt(4)
	v_mfma_f32_32x32x16_bf16 v[16:31], v[104:107], v[220:223], v[16:31]
	v_mfma_f32_32x32x16_bf16 v[16:31], v[108:111], v[224:227], v[16:31]
	s_waitcnt lgkmcnt(0)
	v_mfma_f32_32x32x16_bf16 v[16:31], v[112:115], v[236:239], v[16:31]
	v_mfma_f32_32x32x16_bf16 v[16:31], v[116:119], v[240:243], v[16:31]
	s_barrier
	s_waitcnt vmcnt(0)
	ds_write_b128 v167, v[120:123] offset:39936
	ds_write_b128 v131, v[124:127] offset:49152
	ds_write_b128 v169, v[132:135] offset:39936
	v_exp_f32_e32 v32, v32
	v_exp_f32_e32 v48, v48
	v_exp_f32_e32 v33, v33
	v_exp_f32_e32 v49, v49
	v_exp_f32_e32 v34, v34
	v_exp_f32_e32 v50, v50
	v_exp_f32_e32 v35, v35
	v_exp_f32_e32 v51, v51
	v_exp_f32_e32 v36, v36
	v_exp_f32_e32 v52, v52
	v_exp_f32_e32 v37, v37
	v_exp_f32_e32 v53, v53
	v_exp_f32_e32 v38, v38
	v_exp_f32_e32 v54, v54
	v_exp_f32_e32 v39, v39
	v_exp_f32_e32 v55, v55
	v_exp_f32_e32 v40, v40
	v_exp_f32_e32 v56, v56
	v_exp_f32_e32 v41, v41
	v_exp_f32_e32 v57, v57
	v_exp_f32_e32 v42, v42
	v_exp_f32_e32 v58, v58
	v_exp_f32_e32 v43, v43
	v_exp_f32_e32 v59, v59
	v_exp_f32_e32 v44, v44
	v_exp_f32_e32 v60, v60
	v_exp_f32_e32 v45, v45
	v_exp_f32_e32 v61, v61
	v_exp_f32_e32 v46, v46
	v_exp_f32_e32 v62, v62
	v_exp_f32_e32 v47, v47
	v_exp_f32_e32 v63, v63
	s_waitcnt lgkmcnt(0)
	global_load_dwordx4 v[120:123], v129, s[4:5]
	global_load_dwordx4 v[124:127], v129, s[4:5] offset:128
	global_load_dwordx4 v[132:135], v130, s[6:7]
	s_add_u32 s4, s4, 0x40000
	s_addc_u32 s5, s5, 0
	s_add_u32 s6, s6, 0x1000
	s_addc_u32 s7, s7, 0
	v_add_f32_e32 v175, v32, v33
	v_add_f32_e32 v174, v48, v49
	v_add_f32_e32 v175, v175, v34
	v_add_f32_e32 v174, v174, v50
	v_add_f32_e32 v175, v175, v35
	v_add_f32_e32 v174, v174, v51
	v_add_f32_e32 v175, v175, v36
	v_add_f32_e32 v174, v174, v52
	v_add_f32_e32 v175, v175, v37
	v_add_f32_e32 v174, v174, v53
	v_add_f32_e32 v175, v175, v38
	v_add_f32_e32 v174, v174, v54
	v_add_f32_e32 v175, v175, v39
	v_add_f32_e32 v174, v174, v55
	v_add_f32_e32 v175, v175, v40
	v_add_f32_e32 v174, v174, v56
	v_add_f32_e32 v175, v175, v41
	v_add_f32_e32 v174, v174, v57
	v_add_f32_e32 v175, v175, v42
	v_add_f32_e32 v174, v174, v58
	v_add_f32_e32 v175, v175, v43
	v_add_f32_e32 v174, v174, v59
	v_add_f32_e32 v175, v175, v44
	v_add_f32_e32 v174, v174, v60
	v_add_f32_e32 v175, v175, v45
	v_add_f32_e32 v174, v174, v61
	v_add_f32_e32 v175, v175, v46
	v_add_f32_e32 v174, v174, v62
	v_add_f32_e32 v175, v175, v47
	v_add_f32_e32 v174, v174, v63
	v_add_f32_e32 v175, v175, v174
	v_cmp_ge_f32_e32 vcc, s23, v175
	s_cmp_eq_u64 vcc, exec
	s_cbranch_scc0 .Lat_rare0
; __device__ __forceinline__ void at_qkt(f32x16& p0, f32x16& p1, const char* Ks, const bf16x8* qr, int r32, int hi, float negm) {
; #pragma unroll
;   for (int r = 0; r < 16; ++r) { p0[r] = negm; p1[r] = negm; }
; #pragma unroll
;   for (int d0 = 0; d0 < 6; ++d0) {
;     const bf16x8 b0 = *(const bf16x8*)(Ks + r32 * AT_KROW + d0 * 32 + hi * 16);
;     const bf16x8 b1 = *(const bf16x8*)(Ks + (32 + r32) * AT_KROW + d0 * 32 + hi * 16);
;     p0 = MFMA(b0, qr[d0], p0);
;     p1 = MFMA(b1, qr[d0], p1);
;   }
; }
; __device__ __forceinline__ int v_st(int k, int c) { const int kk = (k & ~0xC) | ((k & 4) << 1) | ((k & 8) >> 1); return ((kk >> 3) * 4 + (c >> 5)) * 512 + ((kk & 7) * 32 + (c & 31)) * 2; }
; __device__ __forceinline__ int v_rd_base(int lane) { return ((lane & 3) << 3) | (((lane >> 2) & 3) << 6) | (((lane >> 4) & 1) << 5) | (((lane >> 5) & 1) << 8); }
; template <int OFF> __device__ __forceinline__ s16x4 tr_read(int vb) {
;   s16x4 r; asm volatile("ds_read_b64_tr_b16 %0, %1 offset:%2" : "=&v"(r) : "v"(vb), "i"(OFF) : "memory"); return r;
; }
; template <int D0> __device__ __forceinline__ void pv_one(f32x16& od, int vb, bf16x8 pa0, bf16x8 pa1, bf16x8 pa2, bf16x8 pa3) {
;   const s16x4 l0 = tr_read<v_rd_off(D0, 0, 0)>(vb), h0 = tr_read<v_rd_off(D0, 0, 1)>(vb), l1 = tr_read<v_rd_off(D0, 1, 0)>(vb), h1 = tr_read<v_rd_off(D0, 1, 1)>(vb);
;   const s16x4 l2 = tr_read<v_rd_off(D0, 2, 0)>(vb), h2 = tr_read<v_rd_off(D0, 2, 1)>(vb), l3 = tr_read<v_rd_off(D0, 3, 0)>(vb), h3 = tr_read<v_rd_off(D0, 3, 1)>(vb);
;   asm volatile("s_waitcnt lgkmcnt(0)" ::: "memory"); SBAR();
;     ...
;   od = MFMA(pa0, PK(l0, h0), od);
;   od = MFMA(pa1, PK(l1, h1), od);
;   od = MFMA(pa2, PK(l2, h2), od);
;   od = MFMA(pa3, PK(l3, h3), od);
;     ...
; }
; __device__ void phase_attn(const Params& p, char* lds) {
;     ...
;     for (int j = 1; j + 1 < NT; j += 2) {
;       SBAR(); at_qkt(pB0, pB1, K_lds + AT_SHMK, qr, r32, hi, -m_reg);
;       at_finishSM(pA0, pA1, alA, l_reg, pa0, pa1, pa2, pa3); SBAR();
;       SLOAD(1, (j + 2) * 64); SBAR();
;       pv_d0(o, vb0, pa0, pa1, pa2, pa3); at_partialSM(pB0, pB1, m_reg, alB, false);
;       __syncthreads(); SWAIT(); SWRITE(0, 0);
;       RESC(alB); __syncthreads();
;       SBAR(); at_qkt(pA0, pA1, K_lds, qr, r32, hi, -m_reg);
;       at_finishSM(pB0, pB1, alB, l_reg, pa0, pa1, pa2, pa3); SBAR();
;       if (j + 3 < NT) SLOAD(0, (j + 3) * 64); SBAR();
.Lat_rare0_back:
	v_add_f32_e32 v173, v173, v175
	v_cvt_pk_bf16_f32 v104, v32, v33
	v_cvt_pk_bf16_f32 v105, v34, v35
	v_cvt_pk_bf16_f32 v106, v36, v37
	v_cvt_pk_bf16_f32 v107, v38, v39
	v_cvt_pk_bf16_f32 v108, v40, v41
	v_cvt_pk_bf16_f32 v109, v42, v43
	v_cvt_pk_bf16_f32 v110, v44, v45
	v_cvt_pk_bf16_f32 v111, v46, v47
	v_cvt_pk_bf16_f32 v112, v48, v49
	v_cvt_pk_bf16_f32 v113, v50, v51
	v_cvt_pk_bf16_f32 v114, v52, v53
	v_cvt_pk_bf16_f32 v115, v54, v55
	v_cvt_pk_bf16_f32 v116, v56, v57
	v_cvt_pk_bf16_f32 v117, v58, v59
	v_cvt_pk_bf16_f32 v118, v60, v61
	v_cvt_pk_bf16_f32 v119, v62, v63
	ds_read_b128 v[184:187], v170 offset:26624
	ds_read_b128 v[188:191], v170 offset:33280
	ds_read_b128 v[192:195], v170 offset:26656
	ds_read_b128 v[196:199], v170 offset:33312
	s_barrier
	ds_read_b128 v[200:203], v170 offset:26688
	ds_read_b128 v[204:207], v170 offset:33344
	s_waitcnt lgkmcnt(4)
	v_mfma_f32_32x32x16_bf16 v[32:47], v[184:187], v[80:83], v[64:79]
	v_mfma_f32_32x32x16_bf16 v[48:63], v[188:191], v[80:83], v[64:79]
	ds_read_b128 v[208:211], v170 offset:26720
	ds_read_b128 v[212:215], v170 offset:33376
	s_waitcnt lgkmcnt(4)
	v_mfma_f32_32x32x16_bf16 v[32:47], v[192:195], v[84:87], v[32:47]
	v_mfma_f32_32x32x16_bf16 v[48:63], v[196:199], v[84:87], v[48:63]
	ds_read_b128 v[184:187], v170 offset:26752
	ds_read_b128 v[188:191], v170 offset:33408
	s_waitcnt lgkmcnt(4)
	v_mfma_f32_32x32x16_bf16 v[32:47], v[200:203], v[88:91], v[32:47]
	v_mfma_f32_32x32x16_bf16 v[48:63], v[204:207], v[88:91], v[48:63]
	ds_read_b128 v[192:195], v170 offset:26784
	ds_read_b128 v[196:199], v170 offset:33440
	s_waitcnt lgkmcnt(4)
	v_mfma_f32_32x32x16_bf16 v[32:47], v[208:211], v[92:95], v[32:47]
	v_mfma_f32_32x32x16_bf16 v[48:63], v[212:215], v[92:95], v[48:63]
	ds_read_b64_tr_b16 v[148:149], v171 offset:16384
	ds_read_b64_tr_b16 v[150:151], v171 offset:18432
	ds_read_b64_tr_b16 v[152:153], v171 offset:20480
	ds_read_b64_tr_b16 v[154:155], v171 offset:22528
	s_waitcnt lgkmcnt(6)
	v_mfma_f32_32x32x16_bf16 v[32:47], v[184:187], v[96:99], v[32:47]
	v_mfma_f32_32x32x16_bf16 v[48:63], v[188:191], v[96:99], v[48:63]
	ds_read_b64_tr_b16 v[156:157], v171 offset:24576
	ds_read_b64_tr_b16 v[158:159], v171 offset:26624
	ds_read_b64_tr_b16 v[216:217], v171 offset:28672
	ds_read_b64_tr_b16 v[218:219], v171 offset:30720
	s_waitcnt lgkmcnt(8)
	v_mfma_f32_32x32x16_bf16 v[32:47], v[192:195], v[100:103], v[32:47]
	v_mfma_f32_32x32x16_bf16 v[48:63], v[196:199], v[100:103], v[48:63]
	ds_read_b64_tr_b16 v[220:221], v171 offset:16896
	ds_read_b64_tr_b16 v[222:223], v171 offset:18944
	ds_read_b64_tr_b16 v[224:225], v171 offset:20992
	ds_read_b64_tr_b16 v[226:227], v171 offset:23040
	s_waitcnt lgkmcnt(8)
	v_mfma_f32_32x32x16_bf16 v[0:15], v[104:107], v[148:151], v[0:15]
	v_mfma_f32_32x32x16_bf16 v[0:15], v[108:111], v[152:155], v[0:15]
	ds_read_b64_tr_b16 v[236:237], v171 offset:25088
	ds_read_b64_tr_b16 v[238:239], v171 offset:27136
	ds_read_b64_tr_b16 v[240:241], v171 offset:29184
	ds_read_b64_tr_b16 v[242:243], v171 offset:31232
	s_waitcnt lgkmcnt(8)
	v_mfma_f32_32x32x16_bf16 v[0:15], v[112:115], v[156:159], v[0:15]
	v_mfma_f32_32x32x16_bf16 v[0:15], v[116:119], v[216:219], v[0:15]
	s_waitcnt lgkmcnt(4)
	v_mfma_f32_32x32x16_bf16 v[16:31], v[104:107], v[220:223], v[16:31]
	v_mfma_f32_32x32x16_bf16 v[16:31], v[108:111], v[224:227], v[16:31]
	s_waitcnt lgkmcnt(0)
	v_mfma_f32_32x32x16_bf16 v[16:31], v[112:115], v[236:239], v[16:31]
	v_mfma_f32_32x32x16_bf16 v[16:31], v[116:119], v[240:243], v[16:31]
	s_barrier
	s_waitcnt vmcnt(0)
	ds_write_b128 v167, v[120:123] offset:0
	ds_write_b128 v131, v[124:127] offset:0
	ds_write_b128 v169, v[132:135] offset:0
	v_exp_f32_e32 v32, v32
	v_exp_f32_e32 v48, v48
	v_exp_f32_e32 v33, v33
	v_exp_f32_e32 v49, v49
	v_exp_f32_e32 v34, v34
	v_exp_f32_e32 v50, v50
	v_exp_f32_e32 v35, v35
	v_exp_f32_e32 v51, v51
	v_exp_f32_e32 v36, v36
	v_exp_f32_e32 v52, v52
	v_exp_f32_e32 v37, v37
	v_exp_f32_e32 v53, v53
	v_exp_f32_e32 v38, v38
	v_exp_f32_e32 v54, v54
	v_exp_f32_e32 v39, v39
	v_exp_f32_e32 v55, v55
	v_exp_f32_e32 v40, v40
	v_exp_f32_e32 v56, v56
	v_exp_f32_e32 v41, v41
	v_exp_f32_e32 v57, v57
	v_exp_f32_e32 v42, v42
	v_exp_f32_e32 v58, v58
	v_exp_f32_e32 v43, v43
	v_exp_f32_e32 v59, v59
	v_exp_f32_e32 v44, v44
	v_exp_f32_e32 v60, v60
	v_exp_f32_e32 v45, v45
	v_exp_f32_e32 v61, v61
	v_exp_f32_e32 v46, v46
	v_exp_f32_e32 v62, v62
	v_exp_f32_e32 v47, v47
	v_exp_f32_e32 v63, v63
	s_waitcnt lgkmcnt(0)
	global_load_dwordx4 v[120:123], v129, s[4:5]
	global_load_dwordx4 v[124:127], v129, s[4:5] offset:128
	global_load_dwordx4 v[132:135], v130, s[6:7]
	s_add_u32 s4, s4, 0x40000
	s_addc_u32 s5, s5, 0
	s_add_u32 s6, s6, 0x1000
	s_addc_u32 s7, s7, 0
	v_add_f32_e32 v175, v32, v33
	v_add_f32_e32 v174, v48, v49
	v_add_f32_e32 v175, v175, v34
	v_add_f32_e32 v174, v174, v50
	v_add_f32_e32 v175, v175, v35
	v_add_f32_e32 v174, v174, v51
	v_add_f32_e32 v175, v175, v36
	v_add_f32_e32 v174, v174, v52
	v_add_f32_e32 v175, v175, v37
	v_add_f32_e32 v174, v174, v53
	v_add_f32_e32 v175, v175, v38
	v_add_f32_e32 v174, v174, v54
	v_add_f32_e32 v175, v175, v39
	v_add_f32_e32 v174, v174, v55
	v_add_f32_e32 v175, v175, v40
	v_add_f32_e32 v174, v174, v56
	v_add_f32_e32 v175, v175, v41
	v_add_f32_e32 v174, v174, v57
	v_add_f32_e32 v175, v175, v42
	v_add_f32_e32 v174, v174, v58
	v_add_f32_e32 v175, v175, v43
	v_add_f32_e32 v174, v174, v59
	v_add_f32_e32 v175, v175, v44
	v_add_f32_e32 v174, v174, v60
	v_add_f32_e32 v175, v175, v45
	v_add_f32_e32 v174, v174, v61
	v_add_f32_e32 v175, v175, v46
	v_add_f32_e32 v174, v174, v62
	v_add_f32_e32 v175, v175, v47
	v_add_f32_e32 v174, v174, v63
	v_add_f32_e32 v175, v175, v174
	v_cmp_ge_f32_e32 vcc, s23, v175
	s_cmp_eq_u64 vcc, exec
	s_cbranch_scc0 .Lat_rare1
; __device__ __forceinline__ void at_qkt(f32x16& p0, f32x16& p1, const char* Ks, const bf16x8* qr, int r32, int hi, float negm) {
; #pragma unroll
;   for (int r = 0; r < 16; ++r) { p0[r] = negm; p1[r] = negm; }
; #pragma unroll
;   for (int d0 = 0; d0 < 6; ++d0) {
;     const bf16x8 b0 = *(const bf16x8*)(Ks + r32 * AT_KROW + d0 * 32 + hi * 16);
;     const bf16x8 b1 = *(const bf16x8*)(Ks + (32 + r32) * AT_KROW + d0 * 32 + hi * 16);
;     p0 = MFMA(b0, qr[d0], p0);
;     p1 = MFMA(b1, qr[d0], p1);
;   }
; }
; __device__ __forceinline__ int v_st(int k, int c) { const int kk = (k & ~0xC) | ((k & 4) << 1) | ((k & 8) >> 1); return ((kk >> 3) * 4 + (c >> 5)) * 512 + ((kk & 7) * 32 + (c & 31)) * 2; }
; __device__ __forceinline__ int v_rd_base(int lane) { return ((lane & 3) << 3) | (((lane >> 2) & 3) << 6) | (((lane >> 4) & 1) << 5) | (((lane >> 5) & 1) << 8); }
; template <int OFF> __device__ __forceinline__ s16x4 tr_read(int vb) {
;   s16x4 r; asm volatile("ds_read_b64_tr_b16 %0, %1 offset:%2" : "=&v"(r) : "v"(vb), "i"(OFF) : "memory"); return r;
; }
; template <int D0> __device__ __forceinline__ void pv_one(f32x16& od, int vb, bf16x8 pa0, bf16x8 pa1, bf16x8 pa2, bf16x8 pa3) {
;   const s16x4 l0 = tr_read<v_rd_off(D0, 0, 0)>(vb), h0 = tr_read<v_rd_off(D0, 0, 1)>(vb), l1 = tr_read<v_rd_off(D0, 1, 0)>(vb), h1 = tr_read<v_rd_off(D0, 1, 1)>(vb);
;   const s16x4 l2 = tr_read<v_rd_off(D0, 2, 0)>(vb), h2 = tr_read<v_rd_off(D0, 2, 1)>(vb), l3 = tr_read<v_rd_off(D0, 3, 0)>(vb), h3 = tr_read<v_rd_off(D0, 3, 1)>(vb);
;   asm volatile("s_waitcnt lgkmcnt(0)" ::: "memory"); SBAR();
;     ...
;   od = MFMA(pa0, PK(l0, h0), od);
;   od = MFMA(pa1, PK(l1, h1), od);
;   od = MFMA(pa2, PK(l2, h2), od);
;   od = MFMA(pa3, PK(l3, h3), od);
;     ...
; }
; __device__ void phase_attn(const Params& p, char* lds) {
;     ...
;     for (int j = 1; j + 1 < NT; j += 2) {
;       SBAR(); at_qkt(pB0, pB1, K_lds + AT_SHMK, qr, r32, hi, -m_reg);
;       at_finishSM(pA0, pA1, alA, l_reg, pa0, pa1, pa2, pa3); SBAR();
;       SLOAD(1, (j + 2) * 64); SBAR();
;       pv_d0(o, vb0, pa0, pa1, pa2, pa3); at_partialSM(pB0, pB1, m_reg, alB, false);
;       __syncthreads(); SWAIT(); SWRITE(0, 0);
;       RESC(alB); __syncthreads();
;       SBAR(); at_qkt(pA0, pA1, K_lds, qr, r32, hi, -m_reg);
;       at_finishSM(pB0, pB1, alB, l_reg, pa0, pa1, pa2, pa3); SBAR();
;       if (j + 3 < NT) SLOAD(0, (j + 3) * 64); SBAR();
.Lat_rare1_back:
	v_add_f32_e32 v173, v173, v175
	v_cvt_pk_bf16_f32 v104, v32, v33
	v_cvt_pk_bf16_f32 v105, v34, v35
	v_cvt_pk_bf16_f32 v106, v36, v37
	v_cvt_pk_bf16_f32 v107, v38, v39
	v_cvt_pk_bf16_f32 v108, v40, v41
	v_cvt_pk_bf16_f32 v109, v42, v43
	v_cvt_pk_bf16_f32 v110, v44, v45
	v_cvt_pk_bf16_f32 v111, v46, v47
	v_cvt_pk_bf16_f32 v112, v48, v49
	v_cvt_pk_bf16_f32 v113, v50, v51
	v_cvt_pk_bf16_f32 v114, v52, v53
	v_cvt_pk_bf16_f32 v115, v54, v55
	v_cvt_pk_bf16_f32 v116, v56, v57
	v_cvt_pk_bf16_f32 v117, v58, v59
	v_cvt_pk_bf16_f32 v118, v60, v61
	v_cvt_pk_bf16_f32 v119, v62, v63
	ds_read_b128 v[184:187], v170 offset:39936
	ds_read_b128 v[188:191], v170 offset:46592
	ds_read_b128 v[192:195], v170 offset:39968
	ds_read_b128 v[196:199], v170 offset:46624
	s_barrier
	ds_read_b128 v[200:203], v170 offset:40000
	ds_read_b128 v[204:207], v170 offset:46656
	s_waitcnt lgkmcnt(4)
	v_mfma_f32_32x32x16_bf16 v[32:47], v[184:187], v[80:83], v[64:79]
	v_mfma_f32_32x32x16_bf16 v[48:63], v[188:191], v[80:83], v[64:79]
	ds_read_b128 v[208:211], v170 offset:40032
	ds_read_b128 v[212:215], v170 offset:46688
	s_waitcnt lgkmcnt(4)
	v_mfma_f32_32x32x16_bf16 v[32:47], v[192:195], v[84:87], v[32:47]
	v_mfma_f32_32x32x16_bf16 v[48:63], v[196:199], v[84:87], v[48:63]
	ds_read_b128 v[184:187], v170 offset:40064
	ds_read_b128 v[188:191], v170 offset:46720
	s_waitcnt lgkmcnt(4)
	v_mfma_f32_32x32x16_bf16 v[32:47], v[200:203], v[88:91], v[32:47]
	v_mfma_f32_32x32x16_bf16 v[48:63], v[204:207], v[88:91], v[48:63]
	ds_read_b128 v[192:195], v170 offset:40096
	ds_read_b128 v[196:199], v170 offset:46752
	s_waitcnt lgkmcnt(4)
	v_mfma_f32_32x32x16_bf16 v[32:47], v[208:211], v[92:95], v[32:47]
	v_mfma_f32_32x32x16_bf16 v[48:63], v[212:215], v[92:95], v[48:63]
	ds_read_b64_tr_b16 v[148:149], v171 offset:32768
	ds_read_b64_tr_b16 v[150:151], v171 offset:34816
	ds_read_b64_tr_b16 v[152:153], v171 offset:36864
	ds_read_b64_tr_b16 v[154:155], v171 offset:38912
	s_waitcnt lgkmcnt(6)
	v_mfma_f32_32x32x16_bf16 v[32:47], v[184:187], v[96:99], v[32:47]
	v_mfma_f32_32x32x16_bf16 v[48:63], v[188:191], v[96:99], v[48:63]
	ds_read_b64_tr_b16 v[156:157], v171 offset:40960
	ds_read_b64_tr_b16 v[158:159], v171 offset:43008
	ds_read_b64_tr_b16 v[216:217], v171 offset:45056
	ds_read_b64_tr_b16 v[218:219], v171 offset:47104
	s_waitcnt lgkmcnt(8)
	v_mfma_f32_32x32x16_bf16 v[32:47], v[192:195], v[100:103], v[32:47]
	v_mfma_f32_32x32x16_bf16 v[48:63], v[196:199], v[100:103], v[48:63]
	ds_read_b64_tr_b16 v[220:221], v171 offset:33280
	ds_read_b64_tr_b16 v[222:223], v171 offset:35328
	ds_read_b64_tr_b16 v[224:225], v171 offset:37376
	ds_read_b64_tr_b16 v[226:227], v171 offset:39424
	s_waitcnt lgkmcnt(8)
	v_mfma_f32_32x32x16_bf16 v[0:15], v[104:107], v[148:151], v[0:15]
	v_mfma_f32_32x32x16_bf16 v[0:15], v[108:111], v[152:155], v[0:15]
	ds_read_b64_tr_b16 v[236:237], v171 offset:41472
	ds_read_b64_tr_b16 v[238:239], v171 offset:43520
	ds_read_b64_tr_b16 v[240:241], v171 offset:45568
	ds_read_b64_tr_b16 v[242:243], v171 offset:47616
	s_waitcnt lgkmcnt(8)
	v_mfma_f32_32x32x16_bf16 v[0:15], v[112:115], v[156:159], v[0:15]
	v_mfma_f32_32x32x16_bf16 v[0:15], v[116:119], v[216:219], v[0:15]
	s_waitcnt lgkmcnt(4)
	v_mfma_f32_32x32x16_bf16 v[16:31], v[104:107], v[220:223], v[16:31]
	v_mfma_f32_32x32x16_bf16 v[16:31], v[108:111], v[224:227], v[16:31]
	s_waitcnt lgkmcnt(0)
	v_mfma_f32_32x32x16_bf16 v[16:31], v[112:115], v[236:239], v[16:31]
	v_mfma_f32_32x32x16_bf16 v[16:31], v[116:119], v[240:243], v[16:31]
	s_barrier
	s_waitcnt vmcnt(0)
	ds_write_b128 v167, v[120:123] offset:13312
	ds_write_b128 v131, v[124:127] offset:16384
	ds_write_b128 v169, v[132:135] offset:13312
	v_exp_f32_e32 v32, v32
	v_exp_f32_e32 v48, v48
	v_exp_f32_e32 v33, v33
	v_exp_f32_e32 v49, v49
	v_exp_f32_e32 v34, v34
	v_exp_f32_e32 v50, v50
	v_exp_f32_e32 v35, v35
	v_exp_f32_e32 v51, v51
	v_exp_f32_e32 v36, v36
	v_exp_f32_e32 v52, v52
	v_exp_f32_e32 v37, v37
	v_exp_f32_e32 v53, v53
	v_exp_f32_e32 v38, v38
	v_exp_f32_e32 v54, v54
	v_exp_f32_e32 v39, v39
	v_exp_f32_e32 v55, v55
	v_exp_f32_e32 v40, v40
	v_exp_f32_e32 v56, v56
	v_exp_f32_e32 v41, v41
	v_exp_f32_e32 v57, v57
	v_exp_f32_e32 v42, v42
	v_exp_f32_e32 v58, v58
	v_exp_f32_e32 v43, v43
	v_exp_f32_e32 v59, v59
	v_exp_f32_e32 v44, v44
	v_exp_f32_e32 v60, v60
	v_exp_f32_e32 v45, v45
	v_exp_f32_e32 v61, v61
	v_exp_f32_e32 v46, v46
	v_exp_f32_e32 v62, v62
	v_exp_f32_e32 v47, v47
	v_exp_f32_e32 v63, v63
	s_waitcnt lgkmcnt(0)
	global_load_dwordx4 v[120:123], v129, s[4:5]
	global_load_dwordx4 v[124:127], v129, s[4:5] offset:128
	global_load_dwordx4 v[132:135], v130, s[6:7]
	s_add_u32 s4, s4, 0x40000
	s_addc_u32 s5, s5, 0
	s_add_u32 s6, s6, 0x1000
	s_addc_u32 s7, s7, 0
	v_add_f32_e32 v175, v32, v33
	v_add_f32_e32 v174, v48, v49
	v_add_f32_e32 v175, v175, v34
	v_add_f32_e32 v174, v174, v50
	v_add_f32_e32 v175, v175, v35
	v_add_f32_e32 v174, v174, v51
	v_add_f32_e32 v175, v175, v36
	v_add_f32_e32 v174, v174, v52
	v_add_f32_e32 v175, v175, v37
	v_add_f32_e32 v174, v174, v53
	v_add_f32_e32 v175, v175, v38
	v_add_f32_e32 v174, v174, v54
	v_add_f32_e32 v175, v175, v39
	v_add_f32_e32 v174, v174, v55
	v_add_f32_e32 v175, v175, v40
	v_add_f32_e32 v174, v174, v56
	v_add_f32_e32 v175, v175, v41
	v_add_f32_e32 v174, v174, v57
	v_add_f32_e32 v175, v175, v42
	v_add_f32_e32 v174, v174, v58
	v_add_f32_e32 v175, v175, v43
	v_add_f32_e32 v174, v174, v59
	v_add_f32_e32 v175, v175, v44
	v_add_f32_e32 v174, v174, v60
	v_add_f32_e32 v175, v175, v45
	v_add_f32_e32 v174, v174, v61
	v_add_f32_e32 v175, v175, v46
	v_add_f32_e32 v174, v174, v62
	v_add_f32_e32 v175, v175, v47
	v_add_f32_e32 v174, v174, v63
	v_add_f32_e32 v175, v175, v174
	v_cmp_ge_f32_e32 vcc, s23, v175
	s_cmp_eq_u64 vcc, exec
	s_cbranch_scc0 .Lat_rare2
; __device__ __forceinline__ void at_qkt(f32x16& p0, f32x16& p1, const char* Ks, const bf16x8* qr, int r32, int hi, float negm) {
; #pragma unroll
;   for (int r = 0; r < 16; ++r) { p0[r] = negm; p1[r] = negm; }
; #pragma unroll
;   for (int d0 = 0; d0 < 6; ++d0) {
;     const bf16x8 b0 = *(const bf16x8*)(Ks + r32 * AT_KROW + d0 * 32 + hi * 16);
;     const bf16x8 b1 = *(const bf16x8*)(Ks + (32 + r32) * AT_KROW + d0 * 32 + hi * 16);
;     p0 = MFMA(b0, qr[d0], p0);
;     p1 = MFMA(b1, qr[d0], p1);
;   }
; }
; __device__ __forceinline__ int v_st(int k, int c) { const int kk = (k & ~0xC) | ((k & 4) << 1) | ((k & 8) >> 1); return ((kk >> 3) * 4 + (c >> 5)) * 512 + ((kk & 7) * 32 + (c & 31)) * 2; }
; __device__ __forceinline__ int v_rd_base(int lane) { return ((lane & 3) << 3) | (((lane >> 2) & 3) << 6) | (((lane >> 4) & 1) << 5) | (((lane >> 5) & 1) << 8); }
; template <int OFF> __device__ __forceinline__ s16x4 tr_read(int vb) {
;   s16x4 r; asm volatile("ds_read_b64_tr_b16 %0, %1 offset:%2" : "=&v"(r) : "v"(vb), "i"(OFF) : "memory"); return r;
; }
; template <int D0> __device__ __forceinline__ void pv_one(f32x16& od, int vb, bf16x8 pa0, bf16x8 pa1, bf16x8 pa2, bf16x8 pa3) {
;   const s16x4 l0 = tr_read<v_rd_off(D0, 0, 0)>(vb), h0 = tr_read<v_rd_off(D0, 0, 1)>(vb), l1 = tr_read<v_rd_off(D0, 1, 0)>(vb), h1 = tr_read<v_rd_off(D0, 1, 1)>(vb);
;   const s16x4 l2 = tr_read<v_rd_off(D0, 2, 0)>(vb), h2 = tr_read<v_rd_off(D0, 2, 1)>(vb), l3 = tr_read<v_rd_off(D0, 3, 0)>(vb), h3 = tr_read<v_rd_off(D0, 3, 1)>(vb);
;   asm volatile("s_waitcnt lgkmcnt(0)" ::: "memory"); SBAR();
;     ...
;   od = MFMA(pa0, PK(l0, h0), od);
;   od = MFMA(pa1, PK(l1, h1), od);
;   od = MFMA(pa2, PK(l2, h2), od);
;   od = MFMA(pa3, PK(l3, h3), od);
;     ...
; }
; __device__ void phase_attn(const Params& p, char* lds) {
;     ...
;     for (int j = 1; j + 1 < NT; j += 2) {
;       SBAR(); at_qkt(pB0, pB1, K_lds + AT_SHMK, qr, r32, hi, -m_reg);
;       at_finishSM(pA0, pA1, alA, l_reg, pa0, pa1, pa2, pa3); SBAR();
;       SLOAD(1, (j + 2) * 64); SBAR();
;       pv_d0(o, vb0, pa0, pa1, pa2, pa3); at_partialSM(pB0, pB1, m_reg, alB, false);
;       __syncthreads(); SWAIT(); SWRITE(0, 0);
;       RESC(alB); __syncthreads();
;       SBAR(); at_qkt(pA0, pA1, K_lds, qr, r32, hi, -m_reg);
;       at_finishSM(pB0, pB1, alB, l_reg, pa0, pa1, pa2, pa3); SBAR();
;       if (j + 3 < NT) SLOAD(0, (j + 3) * 64); SBAR();
.Lat_rare2_back:
	v_add_f32_e32 v173, v173, v175
	v_cvt_pk_bf16_f32 v104, v32, v33
	v_cvt_pk_bf16_f32 v105, v34, v35
	v_cvt_pk_bf16_f32 v106, v36, v37
	v_cvt_pk_bf16_f32 v107, v38, v39
	v_cvt_pk_bf16_f32 v108, v40, v41
	v_cvt_pk_bf16_f32 v109, v42, v43
	v_cvt_pk_bf16_f32 v110, v44, v45
	v_cvt_pk_bf16_f32 v111, v46, v47
	v_cvt_pk_bf16_f32 v112, v48, v49
	v_cvt_pk_bf16_f32 v113, v50, v51
	v_cvt_pk_bf16_f32 v114, v52, v53
	v_cvt_pk_bf16_f32 v115, v54, v55
	v_cvt_pk_bf16_f32 v116, v56, v57
	v_cvt_pk_bf16_f32 v117, v58, v59
	v_cvt_pk_bf16_f32 v118, v60, v61
	v_cvt_pk_bf16_f32 v119, v62, v63
	ds_read_b128 v[184:187], v170 offset:0
	ds_read_b128 v[188:191], v170 offset:6656
	ds_read_b128 v[192:195], v170 offset:32
	ds_read_b128 v[196:199], v170 offset:6688
	s_barrier
	ds_read_b128 v[200:203], v170 offset:64
	ds_read_b128 v[204:207], v170 offset:6720
	s_waitcnt lgkmcnt(4)
	v_mfma_f32_32x32x16_bf16 v[32:47], v[184:187], v[80:83], v[64:79]
	v_mfma_f32_32x32x16_bf16 v[48:63], v[188:191], v[80:83], v[64:79]
	ds_read_b128 v[208:211], v170 offset:96
	ds_read_b128 v[212:215], v170 offset:6752
	s_waitcnt lgkmcnt(4)
	v_mfma_f32_32x32x16_bf16 v[32:47], v[192:195], v[84:87], v[32:47]
	v_mfma_f32_32x32x16_bf16 v[48:63], v[196:199], v[84:87], v[48:63]
	ds_read_b128 v[184:187], v170 offset:128
	ds_read_b128 v[188:191], v170 offset:6784
	s_waitcnt lgkmcnt(4)
	v_mfma_f32_32x32x16_bf16 v[32:47], v[200:203], v[88:91], v[32:47]
	v_mfma_f32_32x32x16_bf16 v[48:63], v[204:207], v[88:91], v[48:63]
	ds_read_b128 v[192:195], v170 offset:160
	ds_read_b128 v[196:199], v170 offset:6816
	s_waitcnt lgkmcnt(4)
	v_mfma_f32_32x32x16_bf16 v[32:47], v[208:211], v[92:95], v[32:47]
	v_mfma_f32_32x32x16_bf16 v[48:63], v[212:215], v[92:95], v[48:63]
	ds_read_b64_tr_b16 v[148:149], v171 offset:49152
	ds_read_b64_tr_b16 v[150:151], v171 offset:51200
	ds_read_b64_tr_b16 v[152:153], v171 offset:53248
	ds_read_b64_tr_b16 v[154:155], v171 offset:55296
	s_waitcnt lgkmcnt(6)
	v_mfma_f32_32x32x16_bf16 v[32:47], v[184:187], v[96:99], v[32:47]
	v_mfma_f32_32x32x16_bf16 v[48:63], v[188:191], v[96:99], v[48:63]
	ds_read_b64_tr_b16 v[156:157], v171 offset:57344
	ds_read_b64_tr_b16 v[158:159], v171 offset:59392
	ds_read_b64_tr_b16 v[216:217], v171 offset:61440
	ds_read_b64_tr_b16 v[218:219], v171 offset:63488
	s_waitcnt lgkmcnt(8)
	v_mfma_f32_32x32x16_bf16 v[32:47], v[192:195], v[100:103], v[32:47]
	v_mfma_f32_32x32x16_bf16 v[48:63], v[196:199], v[100:103], v[48:63]
	ds_read_b64_tr_b16 v[220:221], v171 offset:49664
	ds_read_b64_tr_b16 v[222:223], v171 offset:51712
	ds_read_b64_tr_b16 v[224:225], v171 offset:53760
	ds_read_b64_tr_b16 v[226:227], v171 offset:55808
	s_waitcnt lgkmcnt(8)
	v_mfma_f32_32x32x16_bf16 v[0:15], v[104:107], v[148:151], v[0:15]
	v_mfma_f32_32x32x16_bf16 v[0:15], v[108:111], v[152:155], v[0:15]
	ds_read_b64_tr_b16 v[236:237], v171 offset:57856
	ds_read_b64_tr_b16 v[238:239], v171 offset:59904
	ds_read_b64_tr_b16 v[240:241], v171 offset:61952
	ds_read_b64_tr_b16 v[242:243], v171 offset:64000
	s_waitcnt lgkmcnt(8)
	v_mfma_f32_32x32x16_bf16 v[0:15], v[112:115], v[156:159], v[0:15]
	v_mfma_f32_32x32x16_bf16 v[0:15], v[116:119], v[216:219], v[0:15]
	s_waitcnt lgkmcnt(4)
	v_mfma_f32_32x32x16_bf16 v[16:31], v[104:107], v[220:223], v[16:31]
	v_mfma_f32_32x32x16_bf16 v[16:31], v[108:111], v[224:227], v[16:31]
	s_waitcnt lgkmcnt(0)
	v_mfma_f32_32x32x16_bf16 v[16:31], v[112:115], v[236:239], v[16:31]
	v_mfma_f32_32x32x16_bf16 v[16:31], v[116:119], v[240:243], v[16:31]
	s_barrier
	s_waitcnt vmcnt(0)
	ds_write_b128 v167, v[120:123] offset:26624
	ds_write_b128 v131, v[124:127] offset:32768
	ds_write_b128 v169, v[132:135] offset:26624
	v_exp_f32_e32 v32, v32
	v_exp_f32_e32 v48, v48
	v_exp_f32_e32 v33, v33
	v_exp_f32_e32 v49, v49
	v_exp_f32_e32 v34, v34
	v_exp_f32_e32 v50, v50
	v_exp_f32_e32 v35, v35
	v_exp_f32_e32 v51, v51
	v_exp_f32_e32 v36, v36
	v_exp_f32_e32 v52, v52
	v_exp_f32_e32 v37, v37
	v_exp_f32_e32 v53, v53
	v_exp_f32_e32 v38, v38
	v_exp_f32_e32 v54, v54
	v_exp_f32_e32 v39, v39
	v_exp_f32_e32 v55, v55
	v_exp_f32_e32 v40, v40
	v_exp_f32_e32 v56, v56
	v_exp_f32_e32 v41, v41
	v_exp_f32_e32 v57, v57
	v_exp_f32_e32 v42, v42
	v_exp_f32_e32 v58, v58
	v_exp_f32_e32 v43, v43
	v_exp_f32_e32 v59, v59
	v_exp_f32_e32 v44, v44
	v_exp_f32_e32 v60, v60
	v_exp_f32_e32 v45, v45
	v_exp_f32_e32 v61, v61
	v_exp_f32_e32 v46, v46
	v_exp_f32_e32 v62, v62
	v_exp_f32_e32 v47, v47
	v_exp_f32_e32 v63, v63
	s_waitcnt lgkmcnt(0)
	global_load_dwordx4 v[120:123], v129, s[4:5]
	global_load_dwordx4 v[124:127], v129, s[4:5] offset:128
	global_load_dwordx4 v[132:135], v130, s[6:7]
	s_add_u32 s4, s4, 0x40000
	s_addc_u32 s5, s5, 0
	s_add_u32 s6, s6, 0x1000
	s_addc_u32 s7, s7, 0
	v_add_f32_e32 v175, v32, v33
	v_add_f32_e32 v174, v48, v49
	v_add_f32_e32 v175, v175, v34
	v_add_f32_e32 v174, v174, v50
	v_add_f32_e32 v175, v175, v35
	v_add_f32_e32 v174, v174, v51
	v_add_f32_e32 v175, v175, v36
	v_add_f32_e32 v174, v174, v52
	v_add_f32_e32 v175, v175, v37
	v_add_f32_e32 v174, v174, v53
	v_add_f32_e32 v175, v175, v38
	v_add_f32_e32 v174, v174, v54
	v_add_f32_e32 v175, v175, v39
	v_add_f32_e32 v174, v174, v55
	v_add_f32_e32 v175, v175, v40
	v_add_f32_e32 v174, v174, v56
	v_add_f32_e32 v175, v175, v41
	v_add_f32_e32 v174, v174, v57
	v_add_f32_e32 v175, v175, v42
	v_add_f32_e32 v174, v174, v58
	v_add_f32_e32 v175, v175, v43
	v_add_f32_e32 v174, v174, v59
	v_add_f32_e32 v175, v175, v44
	v_add_f32_e32 v174, v174, v60
	v_add_f32_e32 v175, v175, v45
	v_add_f32_e32 v174, v174, v61
	v_add_f32_e32 v175, v175, v46
	v_add_f32_e32 v174, v174, v62
	v_add_f32_e32 v175, v175, v47
	v_add_f32_e32 v174, v174, v63
	v_add_f32_e32 v175, v175, v174
	v_cmp_ge_f32_e32 vcc, s23, v175
	s_cmp_eq_u64 vcc, exec
	s_cbranch_scc0 .Lat_rare3
; __device__ __forceinline__ void at_qkt(f32x16& p0, f32x16& p1, const char* Ks, const bf16x8* qr, int r32, int hi, float negm) {
; #pragma unroll
;   for (int r = 0; r < 16; ++r) { p0[r] = negm; p1[r] = negm; }
; #pragma unroll
;   for (int d0 = 0; d0 < 6; ++d0) {
;     const bf16x8 b0 = *(const bf16x8*)(Ks + r32 * AT_KROW + d0 * 32 + hi * 16);
;     const bf16x8 b1 = *(const bf16x8*)(Ks + (32 + r32) * AT_KROW + d0 * 32 + hi * 16);
;     p0 = MFMA(b0, qr[d0], p0);
;     p1 = MFMA(b1, qr[d0], p1);
;   }
; }
; __device__ __forceinline__ int v_st(int k, int c) { const int kk = (k & ~0xC) | ((k & 4) << 1) | ((k & 8) >> 1); return ((kk >> 3) * 4 + (c >> 5)) * 512 + ((kk & 7) * 32 + (c & 31)) * 2; }
; __device__ __forceinline__ int v_rd_base(int lane) { return ((lane & 3) << 3) | (((lane >> 2) & 3) << 6) | (((lane >> 4) & 1) << 5) | (((lane >> 5) & 1) << 8); }
; template <int OFF> __device__ __forceinline__ s16x4 tr_read(int vb) {
;   s16x4 r; asm volatile("ds_read_b64_tr_b16 %0, %1 offset:%2" : "=&v"(r) : "v"(vb), "i"(OFF) : "memory"); return r;
; }
; template <int D0> __device__ __forceinline__ void pv_one(f32x16& od, int vb, bf16x8 pa0, bf16x8 pa1, bf16x8 pa2, bf16x8 pa3) {
;   const s16x4 l0 = tr_read<v_rd_off(D0, 0, 0)>(vb), h0 = tr_read<v_rd_off(D0, 0, 1)>(vb), l1 = tr_read<v_rd_off(D0, 1, 0)>(vb), h1 = tr_read<v_rd_off(D0, 1, 1)>(vb);
;   const s16x4 l2 = tr_read<v_rd_off(D0, 2, 0)>(vb), h2 = tr_read<v_rd_off(D0, 2, 1)>(vb), l3 = tr_read<v_rd_off(D0, 3, 0)>(vb), h3 = tr_read<v_rd_off(D0, 3, 1)>(vb);
;   asm volatile("s_waitcnt lgkmcnt(0)" ::: "memory"); SBAR();
;     ...
;   od = MFMA(pa0, PK(l0, h0), od);
;   od = MFMA(pa1, PK(l1, h1), od);
;   od = MFMA(pa2, PK(l2, h2), od);
;   od = MFMA(pa3, PK(l3, h3), od);
;     ...
; }
; __device__ void phase_attn(const Params& p, char* lds) {
;     ...
;     for (int j = 1; j + 1 < NT; j += 2) {
;       SBAR(); at_qkt(pB0, pB1, K_lds + AT_SHMK, qr, r32, hi, -m_reg);
;       at_finishSM(pA0, pA1, alA, l_reg, pa0, pa1, pa2, pa3); SBAR();
;       SLOAD(1, (j + 2) * 64); SBAR();
;       pv_d0(o, vb0, pa0, pa1, pa2, pa3); at_partialSM(pB0, pB1, m_reg, alB, false);
;       __syncthreads(); SWAIT(); SWRITE(0, 0);
;       RESC(alB); __syncthreads();
;       SBAR(); at_qkt(pA0, pA1, K_lds, qr, r32, hi, -m_reg);
;       at_finishSM(pB0, pB1, alB, l_reg, pa0, pa1, pa2, pa3); SBAR();
;       if (j + 3 < NT) SLOAD(0, (j + 3) * 64); SBAR();
.Lat_rare3_back:
	v_add_f32_e32 v173, v173, v175
	v_cvt_pk_bf16_f32 v104, v32, v33
	v_cvt_pk_bf16_f32 v105, v34, v35
	v_cvt_pk_bf16_f32 v106, v36, v37
	v_cvt_pk_bf16_f32 v107, v38, v39
	v_cvt_pk_bf16_f32 v108, v40, v41
	v_cvt_pk_bf16_f32 v109, v42, v43
	v_cvt_pk_bf16_f32 v110, v44, v45
	v_cvt_pk_bf16_f32 v111, v46, v47
	v_cvt_pk_bf16_f32 v112, v48, v49
	v_cvt_pk_bf16_f32 v113, v50, v51
	v_cvt_pk_bf16_f32 v114, v52, v53
	v_cvt_pk_bf16_f32 v115, v54, v55
	v_cvt_pk_bf16_f32 v116, v56, v57
	v_cvt_pk_bf16_f32 v117, v58, v59
	v_cvt_pk_bf16_f32 v118, v60, v61
	v_cvt_pk_bf16_f32 v119, v62, v63
	ds_read_b128 v[184:187], v170 offset:13312
	ds_read_b128 v[188:191], v170 offset:19968
	ds_read_b128 v[192:195], v170 offset:13344
	ds_read_b128 v[196:199], v170 offset:20000
	s_barrier
	s_sub_u32 s13, s13, 1
	s_cmp_lg_u32 s13, 0
	s_cbranch_scc1 .Lat_loop
	ds_read_b128 v[200:203], v170 offset:13376
	ds_read_b128 v[204:207], v170 offset:20032
	s_waitcnt lgkmcnt(4)
	v_mfma_f32_32x32x16_bf16 v[32:47], v[184:187], v[80:83], v[64:79]
	v_mfma_f32_32x32x16_bf16 v[48:63], v[188:191], v[80:83], v[64:79]
	ds_read_b128 v[208:211], v170 offset:13408
	ds_read_b128 v[212:215], v170 offset:20064
	s_waitcnt lgkmcnt(4)
	v_mfma_f32_32x32x16_bf16 v[32:47], v[192:195], v[84:87], v[32:47]
	v_mfma_f32_32x32x16_bf16 v[48:63], v[196:199], v[84:87], v[48:63]
	ds_read_b128 v[184:187], v170 offset:13440
	ds_read_b128 v[188:191], v170 offset:20096
	s_waitcnt lgkmcnt(4)
	v_mfma_f32_32x32x16_bf16 v[32:47], v[200:203], v[88:91], v[32:47]
	v_mfma_f32_32x32x16_bf16 v[48:63], v[204:207], v[88:91], v[48:63]
	ds_read_b128 v[192:195], v170 offset:13472
	ds_read_b128 v[196:199], v170 offset:20128
	s_waitcnt lgkmcnt(4)
	v_mfma_f32_32x32x16_bf16 v[32:47], v[208:211], v[92:95], v[32:47]
	v_mfma_f32_32x32x16_bf16 v[48:63], v[212:215], v[92:95], v[48:63]
	ds_read_b64_tr_b16 v[148:149], v171 offset:0
	ds_read_b64_tr_b16 v[150:151], v171 offset:2048
	ds_read_b64_tr_b16 v[152:153], v171 offset:4096
	ds_read_b64_tr_b16 v[154:155], v171 offset:6144
	s_waitcnt lgkmcnt(6)
	v_mfma_f32_32x32x16_bf16 v[32:47], v[184:187], v[96:99], v[32:47]
	v_mfma_f32_32x32x16_bf16 v[48:63], v[188:191], v[96:99], v[48:63]
	ds_read_b64_tr_b16 v[156:157], v171 offset:8192
	ds_read_b64_tr_b16 v[158:159], v171 offset:10240
	ds_read_b64_tr_b16 v[216:217], v171 offset:12288
	ds_read_b64_tr_b16 v[218:219], v171 offset:14336
	s_waitcnt lgkmcnt(8)
	v_mfma_f32_32x32x16_bf16 v[32:47], v[192:195], v[100:103], v[32:47]
	v_mfma_f32_32x32x16_bf16 v[48:63], v[196:199], v[100:103], v[48:63]
	ds_read_b64_tr_b16 v[220:221], v171 offset:512
	ds_read_b64_tr_b16 v[222:223], v171 offset:2560
	ds_read_b64_tr_b16 v[224:225], v171 offset:4608
	ds_read_b64_tr_b16 v[226:227], v171 offset:6656
	s_waitcnt lgkmcnt(8)
	v_mfma_f32_32x32x16_bf16 v[0:15], v[104:107], v[148:151], v[0:15]
	v_mfma_f32_32x32x16_bf16 v[0:15], v[108:111], v[152:155], v[0:15]
	ds_read_b64_tr_b16 v[236:237], v171 offset:8704
	ds_read_b64_tr_b16 v[238:239], v171 offset:10752
	ds_read_b64_tr_b16 v[240:241], v171 offset:12800
	ds_read_b64_tr_b16 v[242:243], v171 offset:14848
	s_waitcnt lgkmcnt(8)
	v_mfma_f32_32x32x16_bf16 v[0:15], v[112:115], v[156:159], v[0:15]
	v_mfma_f32_32x32x16_bf16 v[0:15], v[116:119], v[216:219], v[0:15]
	s_waitcnt lgkmcnt(4)
	v_mfma_f32_32x32x16_bf16 v[16:31], v[104:107], v[220:223], v[16:31]
	v_mfma_f32_32x32x16_bf16 v[16:31], v[108:111], v[224:227], v[16:31]
	s_waitcnt lgkmcnt(0)
	v_mfma_f32_32x32x16_bf16 v[16:31], v[112:115], v[236:239], v[16:31]
	v_mfma_f32_32x32x16_bf16 v[16:31], v[116:119], v[240:243], v[16:31]
	s_barrier
	s_waitcnt vmcnt(0)
	ds_write_b128 v167, v[120:123] offset:39936
	ds_write_b128 v131, v[124:127] offset:49152
	ds_write_b128 v169, v[132:135] offset:39936
	v_exp_f32_e32 v32, v32
	v_exp_f32_e32 v48, v48
	v_exp_f32_e32 v33, v33
	v_exp_f32_e32 v49, v49
	v_exp_f32_e32 v34, v34
	v_exp_f32_e32 v50, v50
	v_exp_f32_e32 v35, v35
	v_exp_f32_e32 v51, v51
	v_exp_f32_e32 v36, v36
	v_exp_f32_e32 v52, v52
	v_exp_f32_e32 v37, v37
	v_exp_f32_e32 v53, v53
	v_exp_f32_e32 v38, v38
	v_exp_f32_e32 v54, v54
	v_exp_f32_e32 v39, v39
	v_exp_f32_e32 v55, v55
	v_exp_f32_e32 v40, v40
	v_exp_f32_e32 v56, v56
	v_exp_f32_e32 v41, v41
	v_exp_f32_e32 v57, v57
	v_exp_f32_e32 v42, v42
	v_exp_f32_e32 v58, v58
	v_exp_f32_e32 v43, v43
	v_exp_f32_e32 v59, v59
	v_exp_f32_e32 v44, v44
	v_exp_f32_e32 v60, v60
	v_exp_f32_e32 v45, v45
	v_exp_f32_e32 v61, v61
	v_exp_f32_e32 v46, v46
	v_exp_f32_e32 v62, v62
	v_exp_f32_e32 v47, v47
	v_exp_f32_e32 v63, v63
	s_waitcnt lgkmcnt(0)
	v_add_f32_e32 v175, v32, v33
	v_add_f32_e32 v174, v48, v49
	v_add_f32_e32 v175, v175, v34
	v_add_f32_e32 v174, v174, v50
	v_add_f32_e32 v175, v175, v35
	v_add_f32_e32 v174, v174, v51
	v_add_f32_e32 v175, v175, v36
	v_add_f32_e32 v174, v174, v52
	v_add_f32_e32 v175, v175, v37
	v_add_f32_e32 v174, v174, v53
	v_add_f32_e32 v175, v175, v38
	v_add_f32_e32 v174, v174, v54
	v_add_f32_e32 v175, v175, v39
	v_add_f32_e32 v174, v174, v55
	v_add_f32_e32 v175, v175, v40
	v_add_f32_e32 v174, v174, v56
	v_add_f32_e32 v175, v175, v41
	v_add_f32_e32 v174, v174, v57
	v_add_f32_e32 v175, v175, v42
	v_add_f32_e32 v174, v174, v58
	v_add_f32_e32 v175, v175, v43
	v_add_f32_e32 v174, v174, v59
	v_add_f32_e32 v175, v175, v44
	v_add_f32_e32 v174, v174, v60
	v_add_f32_e32 v175, v175, v45
	v_add_f32_e32 v174, v174, v61
	v_add_f32_e32 v175, v175, v46
	v_add_f32_e32 v174, v174, v62
	v_add_f32_e32 v175, v175, v47
	v_add_f32_e32 v174, v174, v63
	v_add_f32_e32 v175, v175, v174
	v_cmp_ge_f32_e32 vcc, s23, v175
	s_cmp_eq_u64 vcc, exec
	s_cbranch_scc0 .Lat_rare_t129
; #define MFMA(a, b, c) __builtin_amdgcn_mfma_f32_32x32x16_bf16((a), (b), (c), 0, 0, 0)
; #define SBAR() __builtin_amdgcn_sched_barrier(0)
; __device__ __forceinline__ void at_qkt(f32x16& p0, f32x16& p1, const char* Ks, const bf16x8* qr, int r32, int hi, float negm) {
; #pragma unroll
;   for (int r = 0; r < 16; ++r) { p0[r] = negm; p1[r] = negm; }
; #pragma unroll
;   for (int d0 = 0; d0 < 6; ++d0) {
;     const bf16x8 b0 = *(const bf16x8*)(Ks + r32 * AT_KROW + d0 * 32 + hi * 16);
;     const bf16x8 b1 = *(const bf16x8*)(Ks + (32 + r32) * AT_KROW + d0 * 32 + hi * 16);
;     p0 = MFMA(b0, qr[d0], p0);
;     p1 = MFMA(b1, qr[d0], p1);
;   }
; }
; __device__ __forceinline__ int v_st(int k, int c) { const int kk = (k & ~0xC) | ((k & 4) << 1) | ((k & 8) >> 1); return ((kk >> 3) * 4 + (c >> 5)) * 512 + ((kk & 7) * 32 + (c & 31)) * 2; }
; __device__ __forceinline__ int v_rd_base(int lane) { return ((lane & 3) << 3) | (((lane >> 2) & 3) << 6) | (((lane >> 4) & 1) << 5) | (((lane >> 5) & 1) << 8); }
; template <int OFF> __device__ __forceinline__ s16x4 tr_read(int vb) {
;   s16x4 r; asm volatile("ds_read_b64_tr_b16 %0, %1 offset:%2" : "=&v"(r) : "v"(vb), "i"(OFF) : "memory"); return r;
; }
; template <int D0> __device__ __forceinline__ void pv_one(f32x16& od, int vb, bf16x8 pa0, bf16x8 pa1, bf16x8 pa2, bf16x8 pa3) {
;   const s16x4 l0 = tr_read<v_rd_off(D0, 0, 0)>(vb), h0 = tr_read<v_rd_off(D0, 0, 1)>(vb), l1 = tr_read<v_rd_off(D0, 1, 0)>(vb), h1 = tr_read<v_rd_off(D0, 1, 1)>(vb);
;   const s16x4 l2 = tr_read<v_rd_off(D0, 2, 0)>(vb), h2 = tr_read<v_rd_off(D0, 2, 1)>(vb), l3 = tr_read<v_rd_off(D0, 3, 0)>(vb), h3 = tr_read<v_rd_off(D0, 3, 1)>(vb);
;   asm volatile("s_waitcnt lgkmcnt(0)" ::: "memory"); SBAR();
;     ...
;   od = MFMA(pa0, PK(l0, h0), od);
;   od = MFMA(pa1, PK(l1, h1), od);
;   od = MFMA(pa2, PK(l2, h2), od);
;   od = MFMA(pa3, PK(l3, h3), od);
;     ...
; }
; __device__ void phase_attn(const Params& p, char* lds) {
;     ...
;     SBAR(); at_qkt(pB0, pB1, K_lds + AT_SHMK, qr, r32, hi, -m_reg);
;     at_finishSM(pA0, pA1, alA, l_reg, pa0, pa1, pa2, pa3); SBAR();
;     pv_d0(o, vb0, pa0, pa1, pa2, pa3); at_partialSM(pB0, pB1, m_reg, alB, false);
;     __syncthreads(); RESC(alB);
.Lat_rare_t129_back:
	v_add_f32_e32 v173, v173, v175
	v_cvt_pk_bf16_f32 v104, v32, v33
	v_cvt_pk_bf16_f32 v105, v34, v35
	v_cvt_pk_bf16_f32 v106, v36, v37
	v_cvt_pk_bf16_f32 v107, v38, v39
	v_cvt_pk_bf16_f32 v108, v40, v41
	v_cvt_pk_bf16_f32 v109, v42, v43
	v_cvt_pk_bf16_f32 v110, v44, v45
	v_cvt_pk_bf16_f32 v111, v46, v47
	v_cvt_pk_bf16_f32 v112, v48, v49
	v_cvt_pk_bf16_f32 v113, v50, v51
	v_cvt_pk_bf16_f32 v114, v52, v53
	v_cvt_pk_bf16_f32 v115, v54, v55
	v_cvt_pk_bf16_f32 v116, v56, v57
	v_cvt_pk_bf16_f32 v117, v58, v59
	v_cvt_pk_bf16_f32 v118, v60, v61
	v_cvt_pk_bf16_f32 v119, v62, v63
	ds_read_b128 v[184:187], v170 offset:26624
	ds_read_b128 v[188:191], v170 offset:33280
	ds_read_b128 v[192:195], v170 offset:26656
	ds_read_b128 v[196:199], v170 offset:33312
	s_barrier
	ds_read_b128 v[200:203], v170 offset:26688
	ds_read_b128 v[204:207], v170 offset:33344
	s_waitcnt lgkmcnt(4)
	v_mfma_f32_32x32x16_bf16 v[32:47], v[184:187], v[80:83], v[64:79]
	v_mfma_f32_32x32x16_bf16 v[48:63], v[188:191], v[80:83], v[64:79]
	ds_read_b128 v[208:211], v170 offset:26720
	ds_read_b128 v[212:215], v170 offset:33376
	s_waitcnt lgkmcnt(4)
	v_mfma_f32_32x32x16_bf16 v[32:47], v[192:195], v[84:87], v[32:47]
	v_mfma_f32_32x32x16_bf16 v[48:63], v[196:199], v[84:87], v[48:63]
	ds_read_b128 v[184:187], v170 offset:26752
	ds_read_b128 v[188:191], v170 offset:33408
	s_waitcnt lgkmcnt(4)
	v_mfma_f32_32x32x16_bf16 v[32:47], v[200:203], v[88:91], v[32:47]
	v_mfma_f32_32x32x16_bf16 v[48:63], v[204:207], v[88:91], v[48:63]
	ds_read_b128 v[192:195], v170 offset:26784
	ds_read_b128 v[196:199], v170 offset:33440
	s_waitcnt lgkmcnt(4)
	v_mfma_f32_32x32x16_bf16 v[32:47], v[208:211], v[92:95], v[32:47]
	v_mfma_f32_32x32x16_bf16 v[48:63], v[212:215], v[92:95], v[48:63]
	ds_read_b64_tr_b16 v[148:149], v171 offset:16384
	ds_read_b64_tr_b16 v[150:151], v171 offset:18432
	ds_read_b64_tr_b16 v[152:153], v171 offset:20480
	ds_read_b64_tr_b16 v[154:155], v171 offset:22528
	s_waitcnt lgkmcnt(6)
	v_mfma_f32_32x32x16_bf16 v[32:47], v[184:187], v[96:99], v[32:47]
	v_mfma_f32_32x32x16_bf16 v[48:63], v[188:191], v[96:99], v[48:63]
	ds_read_b64_tr_b16 v[156:157], v171 offset:24576
	ds_read_b64_tr_b16 v[158:159], v171 offset:26624
	ds_read_b64_tr_b16 v[216:217], v171 offset:28672
	ds_read_b64_tr_b16 v[218:219], v171 offset:30720
	s_waitcnt lgkmcnt(8)
	v_mfma_f32_32x32x16_bf16 v[32:47], v[192:195], v[100:103], v[32:47]
	v_mfma_f32_32x32x16_bf16 v[48:63], v[196:199], v[100:103], v[48:63]
	ds_read_b64_tr_b16 v[220:221], v171 offset:16896
	ds_read_b64_tr_b16 v[222:223], v171 offset:18944
	ds_read_b64_tr_b16 v[224:225], v171 offset:20992
	ds_read_b64_tr_b16 v[226:227], v171 offset:23040
	s_waitcnt lgkmcnt(8)
	v_mfma_f32_32x32x16_bf16 v[0:15], v[104:107], v[148:151], v[0:15]
	v_mfma_f32_32x32x16_bf16 v[0:15], v[108:111], v[152:155], v[0:15]
	ds_read_b64_tr_b16 v[236:237], v171 offset:25088
	ds_read_b64_tr_b16 v[238:239], v171 offset:27136
	ds_read_b64_tr_b16 v[240:241], v171 offset:29184
	ds_read_b64_tr_b16 v[242:243], v171 offset:31232
	s_waitcnt lgkmcnt(8)
	v_mfma_f32_32x32x16_bf16 v[0:15], v[112:115], v[156:159], v[0:15]
	v_mfma_f32_32x32x16_bf16 v[0:15], v[116:119], v[216:219], v[0:15]
	s_waitcnt lgkmcnt(4)
	v_mfma_f32_32x32x16_bf16 v[16:31], v[104:107], v[220:223], v[16:31]
	v_mfma_f32_32x32x16_bf16 v[16:31], v[108:111], v[224:227], v[16:31]
	s_waitcnt lgkmcnt(0)
	v_mfma_f32_32x32x16_bf16 v[16:31], v[112:115], v[236:239], v[16:31]
	v_mfma_f32_32x32x16_bf16 v[16:31], v[116:119], v[240:243], v[16:31]
	s_barrier
	v_exp_f32_e32 v32, v32
	v_exp_f32_e32 v48, v48
	v_exp_f32_e32 v33, v33
	v_exp_f32_e32 v49, v49
	v_exp_f32_e32 v34, v34
	v_exp_f32_e32 v50, v50
	v_exp_f32_e32 v35, v35
	v_exp_f32_e32 v51, v51
	v_exp_f32_e32 v36, v36
	v_exp_f32_e32 v52, v52
	v_exp_f32_e32 v37, v37
	v_exp_f32_e32 v53, v53
	v_exp_f32_e32 v38, v38
	v_exp_f32_e32 v54, v54
	v_exp_f32_e32 v39, v39
	v_exp_f32_e32 v55, v55
	v_exp_f32_e32 v40, v40
	v_exp_f32_e32 v56, v56
	v_exp_f32_e32 v41, v41
	v_exp_f32_e32 v57, v57
	v_exp_f32_e32 v42, v42
	v_exp_f32_e32 v58, v58
	v_exp_f32_e32 v43, v43
	v_exp_f32_e32 v59, v59
	v_exp_f32_e32 v44, v44
	v_exp_f32_e32 v60, v60
	v_exp_f32_e32 v45, v45
	v_exp_f32_e32 v61, v61
	v_exp_f32_e32 v46, v46
	v_exp_f32_e32 v62, v62
	v_exp_f32_e32 v47, v47
	v_exp_f32_e32 v63, v63
	v_add_f32_e32 v175, v32, v33
	v_add_f32_e32 v174, v48, v49
	v_add_f32_e32 v175, v175, v34
	v_add_f32_e32 v174, v174, v50
	v_add_f32_e32 v175, v175, v35
	v_add_f32_e32 v174, v174, v51
	v_add_f32_e32 v175, v175, v36
	v_add_f32_e32 v174, v174, v52
	v_add_f32_e32 v175, v175, v37
	v_add_f32_e32 v174, v174, v53
	v_add_f32_e32 v175, v175, v38
	v_add_f32_e32 v174, v174, v54
	v_add_f32_e32 v175, v175, v39
	v_add_f32_e32 v174, v174, v55
	v_add_f32_e32 v175, v175, v40
	v_add_f32_e32 v174, v174, v56
	v_add_f32_e32 v175, v175, v41
	v_add_f32_e32 v174, v174, v57
	v_add_f32_e32 v175, v175, v42
	v_add_f32_e32 v174, v174, v58
	v_add_f32_e32 v175, v175, v43
	v_add_f32_e32 v174, v174, v59
	v_add_f32_e32 v175, v175, v44
	v_add_f32_e32 v174, v174, v60
	v_add_f32_e32 v175, v175, v45
	v_add_f32_e32 v174, v174, v61
	v_add_f32_e32 v175, v175, v46
	v_add_f32_e32 v174, v174, v62
	v_add_f32_e32 v175, v175, v47
	v_add_f32_e32 v174, v174, v63
	v_add_f32_e32 v175, v175, v174
	v_cmp_ge_f32_e32 vcc, s23, v175
	s_cmp_eq_u64 vcc, exec
	s_cbranch_scc0 .Lat_rare_t130
; #define MFMA(a, b, c) __builtin_amdgcn_mfma_f32_32x32x16_bf16((a), (b), (c), 0, 0, 0)
; #define SBAR() __builtin_amdgcn_sched_barrier(0)
; __device__ __forceinline__ void at_qkt(f32x16& p0, f32x16& p1, const char* Ks, const bf16x8* qr, int r32, int hi, float negm) {
; #pragma unroll
;   for (int r = 0; r < 16; ++r) { p0[r] = negm; p1[r] = negm; }
; #pragma unroll
;   for (int d0 = 0; d0 < 6; ++d0) {
;     const bf16x8 b0 = *(const bf16x8*)(Ks + r32 * AT_KROW + d0 * 32 + hi * 16);
;     const bf16x8 b1 = *(const bf16x8*)(Ks + (32 + r32) * AT_KROW + d0 * 32 + hi * 16);
;     p0 = MFMA(b0, qr[d0], p0);
;     p1 = MFMA(b1, qr[d0], p1);
;   }
; }
; __device__ __forceinline__ int v_st(int k, int c) { const int kk = (k & ~0xC) | ((k & 4) << 1) | ((k & 8) >> 1); return ((kk >> 3) * 4 + (c >> 5)) * 512 + ((kk & 7) * 32 + (c & 31)) * 2; }
; __device__ __forceinline__ int v_rd_base(int lane) { return ((lane & 3) << 3) | (((lane >> 2) & 3) << 6) | (((lane >> 4) & 1) << 5) | (((lane >> 5) & 1) << 8); }
; template <int OFF> __device__ __forceinline__ s16x4 tr_read(int vb) {
;   s16x4 r; asm volatile("ds_read_b64_tr_b16 %0, %1 offset:%2" : "=&v"(r) : "v"(vb), "i"(OFF) : "memory"); return r;
; }
; template <int D0> __device__ __forceinline__ void pv_one(f32x16& od, int vb, bf16x8 pa0, bf16x8 pa1, bf16x8 pa2, bf16x8 pa3) {
;   const s16x4 l0 = tr_read<v_rd_off(D0, 0, 0)>(vb), h0 = tr_read<v_rd_off(D0, 0, 1)>(vb), l1 = tr_read<v_rd_off(D0, 1, 0)>(vb), h1 = tr_read<v_rd_off(D0, 1, 1)>(vb);
;   const s16x4 l2 = tr_read<v_rd_off(D0, 2, 0)>(vb), h2 = tr_read<v_rd_off(D0, 2, 1)>(vb), l3 = tr_read<v_rd_off(D0, 3, 0)>(vb), h3 = tr_read<v_rd_off(D0, 3, 1)>(vb);
;   asm volatile("s_waitcnt lgkmcnt(0)" ::: "memory"); SBAR();
;     ...
;   od = MFMA(pa0, PK(l0, h0), od);
;   od = MFMA(pa1, PK(l1, h1), od);
;   od = MFMA(pa2, PK(l2, h2), od);
;   od = MFMA(pa3, PK(l3, h3), od);
;     ...
; }
; __device__ void phase_attn(const Params& p, char* lds) {
;     ...
;     SBAR(); at_qkt(pB0, pB1, K_lds + AT_SHMK, qr, r32, hi, -m_reg);
;     at_finishSM(pA0, pA1, alA, l_reg, pa0, pa1, pa2, pa3); SBAR();
;     pv_d0(o, vb0, pa0, pa1, pa2, pa3); at_partialSM(pB0, pB1, m_reg, alB, false);
;     __syncthreads(); RESC(alB);
;     at_finishSM(pB0, pB1, alB, l_reg, pa0, pa1, pa2, pa3); SBAR();
;     pv_d0(o, vb0 + AT_SHMV, pa0, pa1, pa2, pa3);
.Lat_rare_t130_back:
	v_add_f32_e32 v173, v173, v175
	v_cvt_pk_bf16_f32 v104, v32, v33
	v_cvt_pk_bf16_f32 v105, v34, v35
	v_cvt_pk_bf16_f32 v106, v36, v37
	v_cvt_pk_bf16_f32 v107, v38, v39
	v_cvt_pk_bf16_f32 v108, v40, v41
	v_cvt_pk_bf16_f32 v109, v42, v43
	v_cvt_pk_bf16_f32 v110, v44, v45
	v_cvt_pk_bf16_f32 v111, v46, v47
	v_cvt_pk_bf16_f32 v112, v48, v49
	v_cvt_pk_bf16_f32 v113, v50, v51
	v_cvt_pk_bf16_f32 v114, v52, v53
	v_cvt_pk_bf16_f32 v115, v54, v55
	v_cvt_pk_bf16_f32 v116, v56, v57
	v_cvt_pk_bf16_f32 v117, v58, v59
	v_cvt_pk_bf16_f32 v118, v60, v61
	v_cvt_pk_bf16_f32 v119, v62, v63
	ds_read_b128 v[184:187], v170 offset:39936
	ds_read_b128 v[188:191], v170 offset:46592
	ds_read_b128 v[192:195], v170 offset:39968
	ds_read_b128 v[196:199], v170 offset:46624
	s_barrier
	ds_read_b128 v[200:203], v170 offset:40000
	ds_read_b128 v[204:207], v170 offset:46656
	s_waitcnt lgkmcnt(4)
	v_mfma_f32_32x32x16_bf16 v[32:47], v[184:187], v[80:83], v[64:79]
	v_mfma_f32_32x32x16_bf16 v[48:63], v[188:191], v[80:83], v[64:79]
	ds_read_b128 v[208:211], v170 offset:40032
	ds_read_b128 v[212:215], v170 offset:46688
	s_waitcnt lgkmcnt(4)
	v_mfma_f32_32x32x16_bf16 v[32:47], v[192:195], v[84:87], v[32:47]
	v_mfma_f32_32x32x16_bf16 v[48:63], v[196:199], v[84:87], v[48:63]
	ds_read_b128 v[184:187], v170 offset:40064
	ds_read_b128 v[188:191], v170 offset:46720
	s_waitcnt lgkmcnt(4)
	v_mfma_f32_32x32x16_bf16 v[32:47], v[200:203], v[88:91], v[32:47]
	v_mfma_f32_32x32x16_bf16 v[48:63], v[204:207], v[88:91], v[48:63]
	ds_read_b128 v[192:195], v170 offset:40096
	ds_read_b128 v[196:199], v170 offset:46752
	s_waitcnt lgkmcnt(4)
	v_mfma_f32_32x32x16_bf16 v[32:47], v[208:211], v[92:95], v[32:47]
	v_mfma_f32_32x32x16_bf16 v[48:63], v[212:215], v[92:95], v[48:63]
	ds_read_b64_tr_b16 v[148:149], v171 offset:32768
	ds_read_b64_tr_b16 v[150:151], v171 offset:34816
	ds_read_b64_tr_b16 v[152:153], v171 offset:36864
	ds_read_b64_tr_b16 v[154:155], v171 offset:38912
	s_waitcnt lgkmcnt(6)
	v_mfma_f32_32x32x16_bf16 v[32:47], v[184:187], v[96:99], v[32:47]
	v_mfma_f32_32x32x16_bf16 v[48:63], v[188:191], v[96:99], v[48:63]
	ds_read_b64_tr_b16 v[156:157], v171 offset:40960
	ds_read_b64_tr_b16 v[158:159], v171 offset:43008
	ds_read_b64_tr_b16 v[216:217], v171 offset:45056
	ds_read_b64_tr_b16 v[218:219], v171 offset:47104
	s_waitcnt lgkmcnt(8)
	v_mfma_f32_32x32x16_bf16 v[32:47], v[192:195], v[100:103], v[32:47]
	v_mfma_f32_32x32x16_bf16 v[48:63], v[196:199], v[100:103], v[48:63]
	ds_read_b64_tr_b16 v[220:221], v171 offset:33280
	ds_read_b64_tr_b16 v[222:223], v171 offset:35328
	ds_read_b64_tr_b16 v[224:225], v171 offset:37376
	ds_read_b64_tr_b16 v[226:227], v171 offset:39424
	s_waitcnt lgkmcnt(8)
	v_mfma_f32_32x32x16_bf16 v[0:15], v[104:107], v[148:151], v[0:15]
	v_mfma_f32_32x32x16_bf16 v[0:15], v[108:111], v[152:155], v[0:15]
	ds_read_b64_tr_b16 v[236:237], v171 offset:41472
	ds_read_b64_tr_b16 v[238:239], v171 offset:43520
	ds_read_b64_tr_b16 v[240:241], v171 offset:45568
	ds_read_b64_tr_b16 v[242:243], v171 offset:47616
	s_waitcnt lgkmcnt(8)
	v_mfma_f32_32x32x16_bf16 v[0:15], v[112:115], v[156:159], v[0:15]
	v_mfma_f32_32x32x16_bf16 v[0:15], v[116:119], v[216:219], v[0:15]
	s_waitcnt lgkmcnt(4)
	v_mfma_f32_32x32x16_bf16 v[16:31], v[104:107], v[220:223], v[16:31]
	v_mfma_f32_32x32x16_bf16 v[16:31], v[108:111], v[224:227], v[16:31]
	s_waitcnt lgkmcnt(0)
	v_mfma_f32_32x32x16_bf16 v[16:31], v[112:115], v[236:239], v[16:31]
	v_mfma_f32_32x32x16_bf16 v[16:31], v[116:119], v[240:243], v[16:31]
	s_barrier
; __device__ __forceinline__ void at_finishSM(f32x16& p0, f32x16& p1, float alpha, float& l_reg, bf16x8& pa0, bf16x8& pa1, bf16x8& pa2, bf16x8& pa3) {
; #pragma unroll
;   for (int r = 0; r < 16; ++r) p1[r] = __builtin_amdgcn_exp2f(p1[r]);
;   float ps = 0;
; #pragma unroll
;   for (int r = 0; r < 16; ++r) ps += p0[r];
; #pragma unroll
;   for (int r = 0; r < 16; ++r) ps += p1[r];
;   { auto rr = __builtin_amdgcn_permlane32_swap(__float_as_uint(ps), __float_as_uint(ps), false, false);
;     ps = __uint_as_float(rr[0]) + __uint_as_float(rr[1]); }
;   l_reg = l_reg * alpha + ps;
;     ...
;   PK4(p0, 0, pa0); PK4(p0, 8, pa1); PK4(p1, 0, pa2); PK4(p1, 8, pa3);
;     ...
; }
; __device__ __forceinline__ void at_qkt(f32x16& p0, f32x16& p1, const char* Ks, const bf16x8* qr, int r32, int hi, float negm) {
; #pragma unroll
;   for (int r = 0; r < 16; ++r) { p0[r] = negm; p1[r] = negm; }
; #pragma unroll
;   for (int d0 = 0; d0 < 6; ++d0) {
;     const bf16x8 b0 = *(const bf16x8*)(Ks + r32 * AT_KROW + d0 * 32 + hi * 16);
;     const bf16x8 b1 = *(const bf16x8*)(Ks + (32 + r32) * AT_KROW + d0 * 32 + hi * 16);
;     p0 = MFMA(b0, qr[d0], p0);
;     p1 = MFMA(b1, qr[d0], p1);
;   }
; }
; __device__ __forceinline__ int v_st(int k, int c) { const int kk = (k & ~0xC) | ((k & 4) << 1) | ((k & 8) >> 1); return ((kk >> 3) * 4 + (c >> 5)) * 512 + ((kk & 7) * 32 + (c & 31)) * 2; }
; __device__ __forceinline__ int v_rd_base(int lane) { return ((lane & 3) << 3) | (((lane >> 2) & 3) << 6) | (((lane >> 4) & 1) << 5) | (((lane >> 5) & 1) << 8); }
; template <int OFF> __device__ __forceinline__ s16x4 tr_read(int vb) {
;   s16x4 r; asm volatile("ds_read_b64_tr_b16 %0, %1 offset:%2" : "=&v"(r) : "v"(vb), "i"(OFF) : "memory"); return r;
; }
; template <int D0> __device__ __forceinline__ void pv_one(f32x16& od, int vb, bf16x8 pa0, bf16x8 pa1, bf16x8 pa2, bf16x8 pa3) {
;   const s16x4 l0 = tr_read<v_rd_off(D0, 0, 0)>(vb), h0 = tr_read<v_rd_off(D0, 0, 1)>(vb), l1 = tr_read<v_rd_off(D0, 1, 0)>(vb), h1 = tr_read<v_rd_off(D0, 1, 1)>(vb);
;   const s16x4 l2 = tr_read<v_rd_off(D0, 2, 0)>(vb), h2 = tr_read<v_rd_off(D0, 2, 1)>(vb), l3 = tr_read<v_rd_off(D0, 3, 0)>(vb), h3 = tr_read<v_rd_off(D0, 3, 1)>(vb);
;   asm volatile("s_waitcnt lgkmcnt(0)" ::: "memory"); SBAR();
;     ...
;   od = MFMA(pa0, PK(l0, h0), od);
;   od = MFMA(pa1, PK(l1, h1), od);
;   od = MFMA(pa2, PK(l2, h2), od);
;   od = MFMA(pa3, PK(l3, h3), od);
;     ...
; }
	s_add_u32 s8, s28, 0x0
	s_addc_u32 s9, s29, 0
	global_load_ushort v120, v235, s[8:9] offset:0
	global_load_ushort v121, v235, s[8:9] offset:64
	global_load_ushort v122, v235, s[8:9] offset:2048
	global_load_ushort v123, v235, s[8:9] offset:2112
	s_add_u32 s8, s28, 0x1000
	s_addc_u32 s9, s29, 0
	global_load_ushort v124, v235, s[8:9] offset:0
	global_load_ushort v125, v235, s[8:9] offset:64
	global_load_ushort v126, v235, s[8:9] offset:2048
	global_load_ushort v127, v235, s[8:9] offset:2112
	s_add_u32 s8, s28, 0x4000
	s_addc_u32 s9, s29, 0
	global_load_ushort v132, v235, s[8:9] offset:0
	global_load_ushort v133, v235, s[8:9] offset:64
	global_load_ushort v134, v235, s[8:9] offset:2048
	global_load_ushort v135, v235, s[8:9] offset:2112
	s_add_u32 s8, s28, 0x5000
	s_addc_u32 s9, s29, 0
	global_load_ushort v136, v235, s[8:9] offset:0
	global_load_ushort v137, v235, s[8:9] offset:64
	global_load_ushort v138, v235, s[8:9] offset:2048
	global_load_ushort v139, v235, s[8:9] offset:2112
	s_add_u32 s8, s28, 0x8000
	s_addc_u32 s9, s29, 0
	global_load_ushort v140, v235, s[8:9] offset:0
	global_load_ushort v141, v235, s[8:9] offset:64
	global_load_ushort v142, v235, s[8:9] offset:2048
	global_load_ushort v143, v235, s[8:9] offset:2112
	s_add_u32 s8, s28, 0x9000
	s_addc_u32 s9, s29, 0
	global_load_ushort v144, v235, s[8:9] offset:0
	global_load_ushort v145, v235, s[8:9] offset:64
	global_load_ushort v146, v235, s[8:9] offset:2048
	global_load_ushort v147, v235, s[8:9] offset:2112
	s_add_u32 s8, s28, 0xc000
	s_addc_u32 s9, s29, 0
	global_load_ushort v200, v235, s[8:9] offset:0
	global_load_ushort v201, v235, s[8:9] offset:64
	global_load_ushort v202, v235, s[8:9] offset:2048
	global_load_ushort v203, v235, s[8:9] offset:2112
	s_add_u32 s8, s28, 0xd000
	s_addc_u32 s9, s29, 0
	global_load_ushort v204, v235, s[8:9] offset:0
	global_load_ushort v205, v235, s[8:9] offset:64
	global_load_ushort v206, v235, s[8:9] offset:2048
	global_load_ushort v207, v235, s[8:9] offset:2112
	v_exp_f32_e32 v32, v32
	v_exp_f32_e32 v48, v48
	v_exp_f32_e32 v33, v33
	v_exp_f32_e32 v49, v49
	v_exp_f32_e32 v34, v34
	v_exp_f32_e32 v50, v50
	v_exp_f32_e32 v35, v35
	v_exp_f32_e32 v51, v51
	v_exp_f32_e32 v36, v36
	v_exp_f32_e32 v52, v52
	v_exp_f32_e32 v37, v37
	v_exp_f32_e32 v53, v53
	v_exp_f32_e32 v38, v38
	v_exp_f32_e32 v54, v54
	v_exp_f32_e32 v39, v39
	v_exp_f32_e32 v55, v55
	v_exp_f32_e32 v40, v40
	v_exp_f32_e32 v56, v56
	v_exp_f32_e32 v41, v41
	v_exp_f32_e32 v57, v57
	v_exp_f32_e32 v42, v42
	v_exp_f32_e32 v58, v58
	v_exp_f32_e32 v43, v43
	v_exp_f32_e32 v59, v59
	v_exp_f32_e32 v44, v44
	v_exp_f32_e32 v60, v60
	v_exp_f32_e32 v45, v45
	v_exp_f32_e32 v61, v61
	v_exp_f32_e32 v46, v46
	v_exp_f32_e32 v62, v62
	v_exp_f32_e32 v47, v47
	v_exp_f32_e32 v63, v63
	v_add_f32_e32 v175, v32, v33
	v_add_f32_e32 v174, v48, v49
	v_add_f32_e32 v175, v175, v34
	v_add_f32_e32 v174, v174, v50
	v_add_f32_e32 v175, v175, v35
	v_add_f32_e32 v174, v174, v51
	v_add_f32_e32 v175, v175, v36
	v_add_f32_e32 v174, v174, v52
	v_add_f32_e32 v175, v175, v37
	v_add_f32_e32 v174, v174, v53
	v_add_f32_e32 v175, v175, v38
	v_add_f32_e32 v174, v174, v54
	v_add_f32_e32 v175, v175, v39
	v_add_f32_e32 v174, v174, v55
	v_add_f32_e32 v175, v175, v40
	v_add_f32_e32 v174, v174, v56
	v_add_f32_e32 v175, v175, v41
	v_add_f32_e32 v174, v174, v57
	v_add_f32_e32 v175, v175, v42
	v_add_f32_e32 v174, v174, v58
	v_add_f32_e32 v175, v175, v43
	v_add_f32_e32 v174, v174, v59
	v_add_f32_e32 v175, v175, v44
	v_add_f32_e32 v174, v174, v60
	v_add_f32_e32 v175, v175, v45
	v_add_f32_e32 v174, v174, v61
	v_add_f32_e32 v175, v175, v46
	v_add_f32_e32 v174, v174, v62
	v_add_f32_e32 v175, v175, v47
	v_add_f32_e32 v174, v174, v63
	v_add_f32_e32 v175, v175, v174
	v_cmp_ge_f32_e32 vcc, s23, v175
	s_cmp_eq_u64 vcc, exec
	s_cbranch_scc0 .Lat_rare_t131
.Lat_rare_t131_back:
	v_add_f32_e32 v173, v173, v175
	v_cvt_pk_bf16_f32 v104, v32, v33
	v_cvt_pk_bf16_f32 v105, v34, v35
	v_cvt_pk_bf16_f32 v106, v36, v37
	v_cvt_pk_bf16_f32 v107, v38, v39
	v_cvt_pk_bf16_f32 v108, v40, v41
	v_cvt_pk_bf16_f32 v109, v42, v43
	v_cvt_pk_bf16_f32 v110, v44, v45
	v_cvt_pk_bf16_f32 v111, v46, v47
	v_cvt_pk_bf16_f32 v112, v48, v49
	v_cvt_pk_bf16_f32 v113, v50, v51
	v_cvt_pk_bf16_f32 v114, v52, v53
	v_cvt_pk_bf16_f32 v115, v54, v55
	v_cvt_pk_bf16_f32 v116, v56, v57
	v_cvt_pk_bf16_f32 v117, v58, v59
	v_cvt_pk_bf16_f32 v118, v60, v61
	v_cvt_pk_bf16_f32 v119, v62, v63
	s_barrier
	ds_read_b64_tr_b16 v[148:149], v171 offset:49152
	ds_read_b64_tr_b16 v[150:151], v171 offset:51200
	ds_read_b64_tr_b16 v[152:153], v171 offset:53248
	ds_read_b64_tr_b16 v[154:155], v171 offset:55296
	ds_read_b64_tr_b16 v[156:157], v171 offset:57344
	ds_read_b64_tr_b16 v[158:159], v171 offset:59392
	ds_read_b64_tr_b16 v[216:217], v171 offset:61440
	ds_read_b64_tr_b16 v[218:219], v171 offset:63488
	ds_read_b64_tr_b16 v[220:221], v171 offset:49664
	ds_read_b64_tr_b16 v[222:223], v171 offset:51712
	ds_read_b64_tr_b16 v[224:225], v171 offset:53760
	ds_read_b64_tr_b16 v[226:227], v171 offset:55808
	s_waitcnt lgkmcnt(8)
	v_mfma_f32_32x32x16_bf16 v[0:15], v[104:107], v[148:151], v[0:15]
	v_mfma_f32_32x32x16_bf16 v[0:15], v[108:111], v[152:155], v[0:15]
	ds_read_b64_tr_b16 v[236:237], v171 offset:57856
	ds_read_b64_tr_b16 v[238:239], v171 offset:59904
	ds_read_b64_tr_b16 v[240:241], v171 offset:61952
	ds_read_b64_tr_b16 v[242:243], v171 offset:64000
	s_waitcnt lgkmcnt(8)
	v_mfma_f32_32x32x16_bf16 v[0:15], v[112:115], v[156:159], v[0:15]
	v_mfma_f32_32x32x16_bf16 v[0:15], v[116:119], v[216:219], v[0:15]
	s_waitcnt lgkmcnt(4)
	v_mfma_f32_32x32x16_bf16 v[16:31], v[104:107], v[220:223], v[16:31]
	v_mfma_f32_32x32x16_bf16 v[16:31], v[108:111], v[224:227], v[16:31]
	s_waitcnt lgkmcnt(0)
	v_mfma_f32_32x32x16_bf16 v[16:31], v[112:115], v[236:239], v[16:31]
	v_mfma_f32_32x32x16_bf16 v[16:31], v[116:119], v[240:243], v[16:31]
	s_cmp_lg_u32 s15, 0
	s_cbranch_scc1 .Lat_nobal
	s_barrier
